# tile-boundary counted waits: first K-tile of a new tile no longer waits for the previous tile's output stores (vmcnt 8->32 on the first two waits of its first iteration) + residual-epilogue waits re-c
# speedup vs baseline: 1.0083x; 1.0057x over previous
.LBB0_166:
	s_mov_b32 vcc_lo, 0
	v_writelane_b32 v251, vcc_lo, 3
	s_mul_i32 s2, s0, 7
	v_writelane_b32 v246, s2, 31
	s_add_i32 s5, s2, 1
	s_and_b32 s2, s0, 1
	v_writelane_b32 v246, s0, 32
	s_bitcmp1_b32 s0, 0
	v_readlane_b32 s6, v248, 40
	v_writelane_b32 v246, s1, 33
	s_cselect_b64 s[0:1], -1, 0
	s_cmp_eq_u32 s2, 0
	s_cselect_b64 s[2:3], -1, 0
	v_writelane_b32 v246, s2, 34
	v_readlane_b32 s7, v248, 41
	s_nop 0
	v_writelane_b32 v246, s3, 35
	s_and_b64 s[2:3], s[2:3], exec
	v_readlane_b32 s2, v250, 8
	v_readlane_b32 s3, v250, 9
	s_cselect_b32 s3, s7, s3
	s_cselect_b32 s2, s6, s2
	v_readlane_b32 s6, v250, 22
	v_writelane_b32 v246, s2, 36
	v_readlane_b32 s7, v250, 23
	s_cmp_le_i32 s6, s5
	v_writelane_b32 v246, s3, 37
	s_cselect_b64 s[2:3], -1, 0
	s_cmp_lt_i32 s5, s7
	s_cselect_b64 s[6:7], -1, 0
	s_and_b64 s[2:3], s[2:3], s[6:7]
	s_and_b64 vcc, exec, s[2:3]
	s_mov_b64 s[2:3], -1
	s_cbranch_vccnz .LBB0_168
	v_readlane_b32 s2, v246, 31
	s_add_i32 s5, s2, 2
	s_mov_b64 s[2:3], 0

.LBB0_177:
	s_ashr_i32 s15, s14, 31
	s_lshl_b64 s[16:17], s[14:15], 19
	v_readlane_b32 s18, v247, 5
	v_readlane_b32 s19, v247, 6
	s_add_u32 s16, s18, s16
	s_addc_u32 s17, s19, s17
	s_and_b64 s[18:19], s[6:7], exec
	s_cselect_b32 s9, s17, s23
	s_cselect_b32 s15, s16, s22
	s_ashr_i32 s13, s12, 31
	s_lshl_b64 s[18:19], s[12:13], 19
	s_add_u32 s18, s44, s18
	s_addc_u32 s19, s43, s19
	s_and_b64 s[30:31], s[6:7], exec
	s_cselect_b32 s13, s19, s27
	s_cselect_b32 s56, s18, s26
	s_add_u32 s22, s22, 0x40080
	s_addc_u32 s23, s23, 0
	s_add_u32 s57, s26, 0x100
	v_mov_b32_e32 v0, 0
	s_addc_u32 s58, s27, 0
	s_mov_b32 s59, -2
	v_mov_b32_e32 v1, v0
	v_mov_b32_e32 v2, v0
	v_mov_b32_e32 v3, v0
	v_mov_b32_e32 v4, v0
	v_mov_b32_e32 v5, v0
	v_mov_b32_e32 v6, v0
	v_mov_b32_e32 v7, v0
	v_mov_b32_e32 v12, v0
	v_mov_b32_e32 v13, v0
	v_mov_b32_e32 v14, v0
	v_mov_b32_e32 v15, v0
	v_mov_b32_e32 v20, v0
	v_mov_b32_e32 v21, v0
	v_mov_b32_e32 v22, v0
	v_mov_b32_e32 v23, v0
	v_mov_b32_e32 v28, v0
	v_mov_b32_e32 v29, v0
	v_mov_b32_e32 v30, v0
	v_mov_b32_e32 v31, v0
	v_mov_b32_e32 v36, v0
	v_mov_b32_e32 v37, v0
	v_mov_b32_e32 v38, v0
	v_mov_b32_e32 v39, v0
	v_mov_b32_e32 v44, v0
	v_mov_b32_e32 v45, v0
	v_mov_b32_e32 v46, v0
	v_mov_b32_e32 v47, v0
	v_mov_b32_e32 v52, v0
	v_mov_b32_e32 v53, v0
	v_mov_b32_e32 v54, v0
	v_mov_b32_e32 v55, v0
	v_mov_b32_e32 v8, v0
	v_mov_b32_e32 v9, v0
	v_mov_b32_e32 v10, v0
	v_mov_b32_e32 v11, v0
	v_mov_b32_e32 v16, v0
	v_mov_b32_e32 v17, v0
	v_mov_b32_e32 v18, v0
	v_mov_b32_e32 v19, v0
	v_mov_b32_e32 v24, v0
	v_mov_b32_e32 v25, v0
	v_mov_b32_e32 v26, v0
	v_mov_b32_e32 v27, v0
	v_mov_b32_e32 v32, v0
	v_mov_b32_e32 v33, v0
	v_mov_b32_e32 v34, v0
	v_mov_b32_e32 v35, v0
	v_mov_b32_e32 v40, v0
	v_mov_b32_e32 v41, v0
	v_mov_b32_e32 v42, v0
	v_mov_b32_e32 v43, v0
	v_mov_b32_e32 v48, v0
	v_mov_b32_e32 v49, v0
	v_mov_b32_e32 v50, v0
	v_mov_b32_e32 v51, v0
	v_mov_b32_e32 v56, v0
	v_mov_b32_e32 v57, v0
	v_mov_b32_e32 v58, v0
	v_mov_b32_e32 v59, v0
	v_mov_b32_e32 v60, v0
	v_mov_b32_e32 v61, v0
	v_mov_b32_e32 v62, v0
	v_mov_b32_e32 v63, v0
	v_mov_b32_e32 v64, v0
	v_mov_b32_e32 v65, v0
	v_mov_b32_e32 v66, v0
	v_mov_b32_e32 v67, v0
	v_mov_b32_e32 v68, v0
	v_mov_b32_e32 v69, v0
	v_mov_b32_e32 v70, v0
	v_mov_b32_e32 v71, v0
	v_mov_b32_e32 v76, v0
	v_mov_b32_e32 v77, v0
	v_mov_b32_e32 v78, v0
	v_mov_b32_e32 v79, v0
	v_mov_b32_e32 v84, v0
	v_mov_b32_e32 v85, v0
	v_mov_b32_e32 v86, v0
	v_mov_b32_e32 v87, v0
	v_mov_b32_e32 v92, v0
	v_mov_b32_e32 v93, v0
	v_mov_b32_e32 v94, v0
	v_mov_b32_e32 v95, v0
	v_mov_b32_e32 v100, v0
	v_mov_b32_e32 v101, v0
	v_mov_b32_e32 v102, v0
	v_mov_b32_e32 v103, v0
	v_mov_b32_e32 v108, v0
	v_mov_b32_e32 v109, v0
	v_mov_b32_e32 v110, v0
	v_mov_b32_e32 v111, v0
	v_mov_b32_e32 v116, v0
	v_mov_b32_e32 v117, v0
	v_mov_b32_e32 v118, v0
	v_mov_b32_e32 v119, v0
	v_mov_b32_e32 v72, v0
	v_mov_b32_e32 v73, v0
	v_mov_b32_e32 v74, v0
	v_mov_b32_e32 v75, v0
	v_mov_b32_e32 v80, v0
	v_mov_b32_e32 v81, v0
	v_mov_b32_e32 v82, v0
	v_mov_b32_e32 v83, v0
	v_mov_b32_e32 v88, v0
	v_mov_b32_e32 v89, v0
	v_mov_b32_e32 v90, v0
	v_mov_b32_e32 v91, v0
	v_mov_b32_e32 v96, v0
	v_mov_b32_e32 v97, v0
	v_mov_b32_e32 v98, v0
	v_mov_b32_e32 v99, v0
	v_mov_b32_e32 v104, v0
	v_mov_b32_e32 v105, v0
	v_mov_b32_e32 v106, v0
	v_mov_b32_e32 v107, v0
	v_mov_b32_e32 v112, v0
	v_mov_b32_e32 v113, v0
	v_mov_b32_e32 v114, v0
	v_mov_b32_e32 v115, v0
	v_mov_b32_e32 v120, v0
	v_mov_b32_e32 v121, v0
	v_mov_b32_e32 v122, v0
	v_mov_b32_e32 v123, v0
	v_mov_b32_e32 v124, v0
	v_mov_b32_e32 v125, v0
	v_mov_b32_e32 v126, v0
	v_mov_b32_e32 v127, v0
	v_readlane_b32 vcc_lo, v251, 3
	s_nop 3
.LBB0_178:
	s_add_u32 s26, s22, 0xfffc0080
	s_addc_u32 s27, s23, -1
	s_add_i32 s34, 0, 0x10000
	s_cmp_eq_u32 s59, 12
	s_cselect_b32 s31, s9, s27
	s_cselect_b32 s30, s15, s26
	s_cselect_b32 s27, s13, s58
	s_cselect_b32 s26, s56, s57
	s_add_i32 s35, 0, 0x14000
	v_add_u32_e32 v140, s34, v195
	v_add_u32_e32 v166, s35, v195
	ds_read_b128 v[128:131], v140
	ds_read_b128 v[132:135], v140 offset:1024
	ds_read_b128 v[136:139], v140 offset:2048
	ds_read_b128 v[140:143], v140 offset:3072
	ds_read_b128 v[144:147], v166
	ds_read_b128 v[148:151], v166 offset:1024
	ds_read_b128 v[180:183], v166 offset:2048
	ds_read_b128 v[184:187], v166 offset:3072
	s_add_i32 m0, s49, 0xc000
	ds_read_b128 v[188:191], v200
	ds_read_b128 v[202:205], v200 offset:1024
	ds_read_b128 v[206:209], v200 offset:2048
	ds_read_b128 v[210:213], v200 offset:3072
	ds_read_b128 v[228:231], v200 offset:4096
	ds_read_b128 v[232:235], v200 offset:5120
	ds_read_b128 v[236:239], v200 offset:6144
	ds_read_b128 v[240:243], v200 offset:7168
	global_load_lds_dwordx4 v160, s[22:23]
	s_add_i32 m0, s49, 0xe000
	s_nop 0
	global_load_lds_dwordx4 v162, s[22:23]
	s_cmp_eq_u32 vcc_lo, 1
	s_cbranch_scc1 .Ltw_178_0
	s_waitcnt vmcnt(8)
.Ltw_178_0:
	s_waitcnt vmcnt(32)
	s_waitcnt lgkmcnt(0)
	s_barrier
	v_mfma_f32_16x16x32_bf16 v[124:127], v[128:131], v[188:191], v[124:127]
	v_mfma_f32_16x16x32_bf16 v[124:127], v[132:135], v[202:205], v[124:127]
	v_mfma_f32_16x16x32_bf16 v[120:123], v[140:143], v[202:205], v[120:123]
	v_mfma_f32_16x16x32_bf16 v[120:123], v[136:139], v[188:191], v[120:123]
	v_mfma_f32_16x16x32_bf16 v[116:119], v[144:147], v[188:191], v[116:119]
	v_mfma_f32_16x16x32_bf16 v[116:119], v[148:151], v[202:205], v[116:119]
	v_mfma_f32_16x16x32_bf16 v[108:111], v[184:187], v[202:205], v[108:111]
	v_mfma_f32_16x16x32_bf16 v[108:111], v[180:183], v[188:191], v[108:111]
	v_mfma_f32_16x16x32_bf16 v[92:95], v[180:183], v[206:209], v[92:95]
	v_mfma_f32_16x16x32_bf16 v[92:95], v[184:187], v[210:213], v[92:95]
	v_mfma_f32_16x16x32_bf16 v[100:103], v[148:151], v[210:213], v[100:103]
	v_mfma_f32_16x16x32_bf16 v[100:103], v[144:147], v[206:209], v[100:103]
	v_mfma_f32_16x16x32_bf16 v[104:107], v[136:139], v[206:209], v[104:107]
	v_mfma_f32_16x16x32_bf16 v[104:107], v[140:143], v[210:213], v[104:107]
	v_mfma_f32_16x16x32_bf16 v[112:115], v[132:135], v[210:213], v[112:115]
	v_mfma_f32_16x16x32_bf16 v[112:115], v[128:131], v[206:209], v[112:115]
	v_mfma_f32_16x16x32_bf16 v[96:99], v[128:131], v[228:231], v[96:99]
	v_mfma_f32_16x16x32_bf16 v[96:99], v[132:135], v[232:235], v[96:99]
	v_mfma_f32_16x16x32_bf16 v[88:91], v[140:143], v[232:235], v[88:91]
	v_mfma_f32_16x16x32_bf16 v[88:91], v[136:139], v[228:231], v[88:91]
	v_mfma_f32_16x16x32_bf16 v[84:87], v[144:147], v[228:231], v[84:87]
	v_mfma_f32_16x16x32_bf16 v[84:87], v[148:151], v[232:235], v[84:87]
	v_mfma_f32_16x16x32_bf16 v[76:79], v[184:187], v[232:235], v[76:79]
	v_mfma_f32_16x16x32_bf16 v[76:79], v[180:183], v[228:231], v[76:79]
	v_mfma_f32_16x16x32_bf16 v[64:67], v[180:183], v[236:239], v[64:67]
	v_mfma_f32_16x16x32_bf16 v[64:67], v[184:187], v[240:243], v[64:67]
	v_mfma_f32_16x16x32_bf16 v[68:71], v[148:151], v[240:243], v[68:71]
	v_mfma_f32_16x16x32_bf16 v[68:71], v[144:147], v[236:239], v[68:71]
	v_mfma_f32_16x16x32_bf16 v[72:75], v[136:139], v[236:239], v[72:75]
	v_mfma_f32_16x16x32_bf16 v[72:75], v[140:143], v[240:243], v[72:75]
	v_mfma_f32_16x16x32_bf16 v[80:83], v[132:135], v[240:243], v[80:83]
	v_mfma_f32_16x16x32_bf16 v[80:83], v[128:131], v[236:239], v[80:83]
	s_barrier
	s_add_i32 s34, s34, s45
	s_add_u32 s98, s26, s20
	s_addc_u32 s99, s27, s21
	s_mov_b32 m0, s34
	ds_read_b128 v[188:191], v200 offset:16384
	ds_read_b128 v[202:205], v200 offset:17408
	ds_read_b128 v[206:209], v200 offset:18432
	ds_read_b128 v[210:213], v200 offset:19456
	ds_read_b128 v[228:231], v200 offset:20480
	ds_read_b128 v[232:235], v200 offset:21504
	ds_read_b128 v[236:239], v200 offset:22528
	ds_read_b128 v[240:243], v200 offset:23552
	global_load_lds_dwordx4 v168, s[26:27]
	s_add_i32 m0, s34, 0x2000
	s_add_u32 s36, s26, 0x40000
	s_addc_u32 s37, s27, 0
	s_add_i32 s34, s35, s45
	global_load_lds_dwordx4 v152, s[26:27]
	s_mov_b32 m0, s34
	s_nop 0
	global_load_lds_dwordx4 v168, s[36:37]
	s_add_i32 m0, s34, 0x2000
	s_nop 0
	global_load_lds_dwordx4 v152, s[36:37]
	s_add_u32 s100, s30, s20
	s_addc_u32 s101, s31, s21
	s_mov_b32 m0, s49
	s_nop 0
	global_load_lds_dwordx4 v156, s[30:31]
	s_mov_b32 m0, s50
	s_nop 0
	global_load_lds_dwordx4 v154, s[30:31]
	s_cmp_eq_u32 vcc_lo, 1
	s_cbranch_scc1 .Ltw_178_1
	s_waitcnt vmcnt(8)
.Ltw_178_1:
	s_waitcnt vmcnt(32)
	s_mov_b32 vcc_lo, 0
	s_waitcnt lgkmcnt(0)
	s_barrier
	v_mfma_f32_16x16x32_bf16 v[60:63], v[128:131], v[188:191], v[60:63]
	v_mfma_f32_16x16x32_bf16 v[60:63], v[132:135], v[202:205], v[60:63]
	v_mfma_f32_16x16x32_bf16 v[56:59], v[140:143], v[202:205], v[56:59]
	v_mfma_f32_16x16x32_bf16 v[56:59], v[136:139], v[188:191], v[56:59]
	v_mfma_f32_16x16x32_bf16 v[52:55], v[144:147], v[188:191], v[52:55]
	v_mfma_f32_16x16x32_bf16 v[52:55], v[148:151], v[202:205], v[52:55]
	v_mfma_f32_16x16x32_bf16 v[44:47], v[184:187], v[202:205], v[44:47]
	v_mfma_f32_16x16x32_bf16 v[44:47], v[180:183], v[188:191], v[44:47]
	v_mfma_f32_16x16x32_bf16 v[28:31], v[180:183], v[206:209], v[28:31]
	v_mfma_f32_16x16x32_bf16 v[28:31], v[184:187], v[210:213], v[28:31]
	v_mfma_f32_16x16x32_bf16 v[36:39], v[148:151], v[210:213], v[36:39]
	v_mfma_f32_16x16x32_bf16 v[36:39], v[144:147], v[206:209], v[36:39]
	v_mfma_f32_16x16x32_bf16 v[40:43], v[136:139], v[206:209], v[40:43]
	v_mfma_f32_16x16x32_bf16 v[40:43], v[140:143], v[210:213], v[40:43]
	v_mfma_f32_16x16x32_bf16 v[48:51], v[132:135], v[210:213], v[48:51]
	v_mfma_f32_16x16x32_bf16 v[48:51], v[128:131], v[206:209], v[48:51]
	v_mfma_f32_16x16x32_bf16 v[32:35], v[128:131], v[228:231], v[32:35]
	v_mfma_f32_16x16x32_bf16 v[32:35], v[132:135], v[232:235], v[32:35]
	v_mfma_f32_16x16x32_bf16 v[24:27], v[140:143], v[232:235], v[24:27]
	v_mfma_f32_16x16x32_bf16 v[24:27], v[136:139], v[228:231], v[24:27]
	v_mfma_f32_16x16x32_bf16 v[20:23], v[144:147], v[228:231], v[20:23]
	v_mfma_f32_16x16x32_bf16 v[20:23], v[148:151], v[232:235], v[20:23]
	v_mfma_f32_16x16x32_bf16 v[12:15], v[184:187], v[232:235], v[12:15]
	v_mfma_f32_16x16x32_bf16 v[12:15], v[180:183], v[228:231], v[12:15]
	v_mfma_f32_16x16x32_bf16 v[0:3], v[180:183], v[236:239], v[0:3]
	v_mfma_f32_16x16x32_bf16 v[0:3], v[184:187], v[240:243], v[0:3]
	v_mfma_f32_16x16x32_bf16 v[4:7], v[148:151], v[240:243], v[4:7]
	v_mfma_f32_16x16x32_bf16 v[4:7], v[144:147], v[236:239], v[4:7]
	v_mfma_f32_16x16x32_bf16 v[8:11], v[136:139], v[236:239], v[8:11]
	v_mfma_f32_16x16x32_bf16 v[8:11], v[140:143], v[240:243], v[8:11]
	v_mfma_f32_16x16x32_bf16 v[16:19], v[132:135], v[240:243], v[16:19]
	v_mfma_f32_16x16x32_bf16 v[16:19], v[128:131], v[236:239], v[16:19]
	s_barrier
	s_add_i32 s34, 0, 0x18000
	s_add_i32 s35, 0, 0x1c000
	v_add_u32_e32 v140, s34, v195
	v_add_u32_e32 v184, s35, v195
	ds_read_b128 v[128:131], v140
	ds_read_b128 v[132:135], v140 offset:1024
	ds_read_b128 v[136:139], v140 offset:2048
	ds_read_b128 v[140:143], v140 offset:3072
	ds_read_b128 v[144:147], v184
	ds_read_b128 v[148:151], v184 offset:1024
	ds_read_b128 v[180:183], v184 offset:2048
	ds_read_b128 v[184:187], v184 offset:3072
	s_add_u32 s30, s30, 0x40000
	s_addc_u32 s31, s31, 0
	s_mov_b32 m0, s51
	ds_read_b128 v[188:191], v200 offset:32768
	ds_read_b128 v[202:205], v200 offset:33792
	ds_read_b128 v[206:209], v200 offset:34816
	ds_read_b128 v[210:213], v200 offset:35840
	ds_read_b128 v[228:231], v200 offset:36864
	ds_read_b128 v[232:235], v200 offset:37888
	ds_read_b128 v[236:239], v200 offset:38912
	ds_read_b128 v[240:243], v200 offset:39936
	global_load_lds_dwordx4 v156, s[30:31]
	s_mov_b32 m0, s52
	s_nop 0
	global_load_lds_dwordx4 v154, s[30:31]
	s_waitcnt vmcnt(8)
	s_waitcnt lgkmcnt(0)
	s_barrier
	v_mfma_f32_16x16x32_bf16 v[124:127], v[128:131], v[188:191], v[124:127]
	v_mfma_f32_16x16x32_bf16 v[124:127], v[132:135], v[202:205], v[124:127]
	v_mfma_f32_16x16x32_bf16 v[120:123], v[140:143], v[202:205], v[120:123]
	v_mfma_f32_16x16x32_bf16 v[120:123], v[136:139], v[188:191], v[120:123]
	v_mfma_f32_16x16x32_bf16 v[116:119], v[144:147], v[188:191], v[116:119]
	v_mfma_f32_16x16x32_bf16 v[116:119], v[148:151], v[202:205], v[116:119]
	v_mfma_f32_16x16x32_bf16 v[108:111], v[184:187], v[202:205], v[108:111]
	v_mfma_f32_16x16x32_bf16 v[108:111], v[180:183], v[188:191], v[108:111]
	v_mfma_f32_16x16x32_bf16 v[92:95], v[180:183], v[206:209], v[92:95]
	v_mfma_f32_16x16x32_bf16 v[92:95], v[184:187], v[210:213], v[92:95]
	v_mfma_f32_16x16x32_bf16 v[100:103], v[148:151], v[210:213], v[100:103]
	v_mfma_f32_16x16x32_bf16 v[100:103], v[144:147], v[206:209], v[100:103]
	v_mfma_f32_16x16x32_bf16 v[104:107], v[136:139], v[206:209], v[104:107]
	v_mfma_f32_16x16x32_bf16 v[104:107], v[140:143], v[210:213], v[104:107]
	v_mfma_f32_16x16x32_bf16 v[112:115], v[132:135], v[210:213], v[112:115]
	v_mfma_f32_16x16x32_bf16 v[112:115], v[128:131], v[206:209], v[112:115]
	v_mfma_f32_16x16x32_bf16 v[96:99], v[128:131], v[228:231], v[96:99]
	v_mfma_f32_16x16x32_bf16 v[96:99], v[132:135], v[232:235], v[96:99]
	v_mfma_f32_16x16x32_bf16 v[88:91], v[140:143], v[232:235], v[88:91]
	v_mfma_f32_16x16x32_bf16 v[88:91], v[136:139], v[228:231], v[88:91]
	v_mfma_f32_16x16x32_bf16 v[84:87], v[144:147], v[228:231], v[84:87]
	v_mfma_f32_16x16x32_bf16 v[84:87], v[148:151], v[232:235], v[84:87]
	v_mfma_f32_16x16x32_bf16 v[76:79], v[184:187], v[232:235], v[76:79]
	v_mfma_f32_16x16x32_bf16 v[76:79], v[180:183], v[228:231], v[76:79]
	v_mfma_f32_16x16x32_bf16 v[64:67], v[180:183], v[236:239], v[64:67]
	v_mfma_f32_16x16x32_bf16 v[64:67], v[184:187], v[240:243], v[64:67]
	v_mfma_f32_16x16x32_bf16 v[68:71], v[148:151], v[240:243], v[68:71]
	v_mfma_f32_16x16x32_bf16 v[68:71], v[144:147], v[236:239], v[68:71]
	v_mfma_f32_16x16x32_bf16 v[72:75], v[136:139], v[236:239], v[72:75]
	v_mfma_f32_16x16x32_bf16 v[72:75], v[140:143], v[240:243], v[72:75]
	v_mfma_f32_16x16x32_bf16 v[80:83], v[132:135], v[240:243], v[80:83]
	v_mfma_f32_16x16x32_bf16 v[80:83], v[128:131], v[236:239], v[80:83]
	s_barrier
	s_add_i32 s30, s34, s45
	s_mov_b32 m0, s30
	ds_read_b128 v[188:191], v200 offset:49152
	ds_read_b128 v[202:205], v200 offset:50176
	ds_read_b128 v[206:209], v200 offset:51200
	ds_read_b128 v[210:213], v200 offset:52224
	ds_read_b128 v[228:231], v200 offset:53248
	ds_read_b128 v[232:235], v200 offset:54272
	ds_read_b128 v[236:239], v200 offset:55296
	ds_read_b128 v[240:243], v200 offset:56320
	global_load_lds_dwordx4 v168, s[98:99]
	s_add_i32 m0, s30, 0x2000
	s_add_u32 s26, s26, 0x40080
	s_addc_u32 s27, s27, 0
	s_add_i32 s30, s35, s45
	global_load_lds_dwordx4 v152, s[98:99]
	s_mov_b32 m0, s30
	s_nop 0
	global_load_lds_dwordx4 v168, s[26:27]
	s_add_i32 m0, s30, 0x2000
	s_nop 0
	global_load_lds_dwordx4 v152, s[26:27]
	s_mov_b32 m0, s24
	s_nop 0
	global_load_lds_dwordx4 v156, s[100:101]
	s_mov_b32 m0, s53
	s_nop 0
	global_load_lds_dwordx4 v154, s[100:101]
	s_waitcnt vmcnt(8)
	s_waitcnt lgkmcnt(0)
	s_barrier
	v_mfma_f32_16x16x32_bf16 v[60:63], v[128:131], v[188:191], v[60:63]
	v_mfma_f32_16x16x32_bf16 v[60:63], v[132:135], v[202:205], v[60:63]
	v_mfma_f32_16x16x32_bf16 v[56:59], v[140:143], v[202:205], v[56:59]
	v_mfma_f32_16x16x32_bf16 v[56:59], v[136:139], v[188:191], v[56:59]
	v_mfma_f32_16x16x32_bf16 v[52:55], v[144:147], v[188:191], v[52:55]
	v_mfma_f32_16x16x32_bf16 v[52:55], v[148:151], v[202:205], v[52:55]
	v_mfma_f32_16x16x32_bf16 v[44:47], v[184:187], v[202:205], v[44:47]
	v_mfma_f32_16x16x32_bf16 v[44:47], v[180:183], v[188:191], v[44:47]
	v_mfma_f32_16x16x32_bf16 v[28:31], v[180:183], v[206:209], v[28:31]
	v_mfma_f32_16x16x32_bf16 v[28:31], v[184:187], v[210:213], v[28:31]
	v_mfma_f32_16x16x32_bf16 v[36:39], v[148:151], v[210:213], v[36:39]
	v_mfma_f32_16x16x32_bf16 v[36:39], v[144:147], v[206:209], v[36:39]
	v_mfma_f32_16x16x32_bf16 v[40:43], v[136:139], v[206:209], v[40:43]
	v_mfma_f32_16x16x32_bf16 v[40:43], v[140:143], v[210:213], v[40:43]
	v_mfma_f32_16x16x32_bf16 v[48:51], v[132:135], v[210:213], v[48:51]
	v_mfma_f32_16x16x32_bf16 v[48:51], v[128:131], v[206:209], v[48:51]
	v_mfma_f32_16x16x32_bf16 v[32:35], v[128:131], v[228:231], v[32:35]
	v_mfma_f32_16x16x32_bf16 v[32:35], v[132:135], v[232:235], v[32:35]
	v_mfma_f32_16x16x32_bf16 v[24:27], v[140:143], v[232:235], v[24:27]
	v_mfma_f32_16x16x32_bf16 v[24:27], v[136:139], v[228:231], v[24:27]
	v_mfma_f32_16x16x32_bf16 v[20:23], v[144:147], v[228:231], v[20:23]
	v_mfma_f32_16x16x32_bf16 v[20:23], v[148:151], v[232:235], v[20:23]
	v_mfma_f32_16x16x32_bf16 v[12:15], v[184:187], v[232:235], v[12:15]
	v_mfma_f32_16x16x32_bf16 v[12:15], v[180:183], v[228:231], v[12:15]
	v_mfma_f32_16x16x32_bf16 v[0:3], v[180:183], v[236:239], v[0:3]
	v_mfma_f32_16x16x32_bf16 v[0:3], v[184:187], v[240:243], v[0:3]
	v_mfma_f32_16x16x32_bf16 v[4:7], v[148:151], v[240:243], v[4:7]
	v_mfma_f32_16x16x32_bf16 v[4:7], v[144:147], v[236:239], v[4:7]
	v_mfma_f32_16x16x32_bf16 v[8:11], v[136:139], v[236:239], v[8:11]
	v_mfma_f32_16x16x32_bf16 v[8:11], v[140:143], v[240:243], v[8:11]
	v_mfma_f32_16x16x32_bf16 v[16:19], v[132:135], v[240:243], v[16:19]
	v_mfma_f32_16x16x32_bf16 v[16:19], v[128:131], v[236:239], v[16:19]
	s_barrier
	s_add_i32 s59, s59, 2
	s_add_u32 s22, s22, 0x100
	s_addc_u32 s23, s23, 0
	s_add_u32 s57, s57, 0x100
	s_addc_u32 s58, s58, 0
	s_cmp_gt_u32 s59, 13
	s_cbranch_scc0 .LBB0_178
	s_mov_b32 vcc_lo, 1
	v_writelane_b32 v251, vcc_lo, 3
	s_and_b64 vcc, exec, s[10:11]
	s_cbranch_vccz .LBB0_181
	s_barrier

.LBB0_759:
.LBB0_760:
	s_mov_b32 vcc_lo, 0
	v_writelane_b32 v251, vcc_lo, 3
	v_readlane_b32 s2, v250, 22
	v_readlane_b32 s3, v250, 23
	s_cmp_le_i32 s2, s5
	s_cselect_b64 s[2:3], -1, 0
	s_and_b64 s[2:3], s[2:3], s[0:1]
	s_mov_b64 s[0:1], -1
	s_and_b64 vcc, exec, s[2:3]
	s_cbranch_vccnz .LBB0_762
	v_readlane_b32 s0, v246, 31
	s_add_i32 s5, s0, 6
	s_mov_b64 s[0:1], 0

.LBB0_775:
	s_ashr_i32 s15, s14, 31
	s_lshl_b64 s[16:17], s[14:15], 19
	v_readlane_b32 s18, v250, 10
	v_readlane_b32 s19, v250, 11
	s_add_u32 s16, s18, s16
	s_addc_u32 s17, s19, s17
	s_and_b64 s[18:19], s[8:9], exec
	s_cselect_b32 s15, s17, s23
	s_cselect_b32 s51, s16, s22
	s_ashr_i32 s13, s12, 31
	s_lshl_b64 s[18:19], s[12:13], 19
	s_add_u32 s18, s5, s18
	s_addc_u32 s19, s34, s19
	s_and_b64 s[30:31], s[8:9], exec
	s_cselect_b32 s13, s19, s27
	s_cselect_b32 s52, s18, s26
	s_add_u32 s22, s22, 0x40080
	s_addc_u32 s23, s23, 0
	s_add_u32 s53, s26, 0x100
	v_mov_b32_e32 v0, 0
	s_addc_u32 s54, s27, 0
	s_mov_b32 s55, -2
	s_waitcnt lgkmcnt(0)
	v_mov_b32_e32 v1, v0
	v_mov_b32_e32 v2, v0
	v_mov_b32_e32 v3, v0
	v_mov_b32_e32 v4, v0
	v_mov_b32_e32 v5, v0
	v_mov_b32_e32 v6, v0
	v_mov_b32_e32 v7, v0
	v_mov_b32_e32 v16, v0
	v_mov_b32_e32 v17, v0
	v_mov_b32_e32 v18, v0
	v_mov_b32_e32 v19, v0
	v_mov_b32_e32 v20, v0
	v_mov_b32_e32 v21, v0
	v_mov_b32_e32 v22, v0
	v_mov_b32_e32 v23, v0
	v_mov_b32_e32 v32, v0
	v_mov_b32_e32 v33, v0
	v_mov_b32_e32 v34, v0
	v_mov_b32_e32 v35, v0
	v_mov_b32_e32 v36, v0
	v_mov_b32_e32 v37, v0
	v_mov_b32_e32 v38, v0
	v_mov_b32_e32 v39, v0
	v_mov_b32_e32 v48, v0
	v_mov_b32_e32 v49, v0
	v_mov_b32_e32 v50, v0
	v_mov_b32_e32 v51, v0
	v_mov_b32_e32 v52, v0
	v_mov_b32_e32 v53, v0
	v_mov_b32_e32 v54, v0
	v_mov_b32_e32 v55, v0
	v_mov_b32_e32 v8, v0
	v_mov_b32_e32 v9, v0
	v_mov_b32_e32 v10, v0
	v_mov_b32_e32 v11, v0
	v_mov_b32_e32 v12, v0
	v_mov_b32_e32 v13, v0
	v_mov_b32_e32 v14, v0
	v_mov_b32_e32 v15, v0
	v_mov_b32_e32 v24, v0
	v_mov_b32_e32 v25, v0
	v_mov_b32_e32 v26, v0
	v_mov_b32_e32 v27, v0
	v_mov_b32_e32 v28, v0
	v_mov_b32_e32 v29, v0
	v_mov_b32_e32 v30, v0
	v_mov_b32_e32 v31, v0
	v_mov_b32_e32 v40, v0
	v_mov_b32_e32 v41, v0
	v_mov_b32_e32 v42, v0
	v_mov_b32_e32 v43, v0
	v_mov_b32_e32 v44, v0
	v_mov_b32_e32 v45, v0
	v_mov_b32_e32 v46, v0
	v_mov_b32_e32 v47, v0
	v_mov_b32_e32 v56, v0
	v_mov_b32_e32 v57, v0
	v_mov_b32_e32 v58, v0
	v_mov_b32_e32 v59, v0
	v_mov_b32_e32 v60, v0
	v_mov_b32_e32 v61, v0
	v_mov_b32_e32 v62, v0
	v_mov_b32_e32 v63, v0
	v_mov_b32_e32 v64, v0
	v_mov_b32_e32 v65, v0
	v_mov_b32_e32 v66, v0
	v_mov_b32_e32 v67, v0
	v_mov_b32_e32 v68, v0
	v_mov_b32_e32 v69, v0
	v_mov_b32_e32 v70, v0
	v_mov_b32_e32 v71, v0
	v_mov_b32_e32 v80, v0
	v_mov_b32_e32 v81, v0
	v_mov_b32_e32 v82, v0
	v_mov_b32_e32 v83, v0
	v_mov_b32_e32 v84, v0
	v_mov_b32_e32 v85, v0
	v_mov_b32_e32 v86, v0
	v_mov_b32_e32 v87, v0
	v_mov_b32_e32 v96, v0
	v_mov_b32_e32 v97, v0
	v_mov_b32_e32 v98, v0
	v_mov_b32_e32 v99, v0
	v_mov_b32_e32 v100, v0
	v_mov_b32_e32 v101, v0
	v_mov_b32_e32 v102, v0
	v_mov_b32_e32 v103, v0
	v_mov_b32_e32 v112, v0
	v_mov_b32_e32 v113, v0
	v_mov_b32_e32 v114, v0
	v_mov_b32_e32 v115, v0
	v_mov_b32_e32 v116, v0
	v_mov_b32_e32 v117, v0
	v_mov_b32_e32 v118, v0
	v_mov_b32_e32 v119, v0
	v_mov_b32_e32 v72, v0
	v_mov_b32_e32 v73, v0
	v_mov_b32_e32 v74, v0
	v_mov_b32_e32 v75, v0
	v_mov_b32_e32 v76, v0
	v_mov_b32_e32 v77, v0
	v_mov_b32_e32 v78, v0
	v_mov_b32_e32 v79, v0
	v_mov_b32_e32 v88, v0
	v_mov_b32_e32 v89, v0
	v_mov_b32_e32 v90, v0
	v_mov_b32_e32 v91, v0
	v_mov_b32_e32 v92, v0
	v_mov_b32_e32 v93, v0
	v_mov_b32_e32 v94, v0
	v_mov_b32_e32 v95, v0
	v_mov_b32_e32 v104, v0
	v_mov_b32_e32 v105, v0
	v_mov_b32_e32 v106, v0
	v_mov_b32_e32 v107, v0
	v_mov_b32_e32 v108, v0
	v_mov_b32_e32 v109, v0
	v_mov_b32_e32 v110, v0
	v_mov_b32_e32 v111, v0
	v_mov_b32_e32 v120, v0
	v_mov_b32_e32 v121, v0
	v_mov_b32_e32 v122, v0
	v_mov_b32_e32 v123, v0
	v_mov_b32_e32 v124, v0
	v_mov_b32_e32 v125, v0
	v_mov_b32_e32 v126, v0
	v_mov_b32_e32 v127, v0
	v_readlane_b32 vcc_lo, v251, 3
	s_nop 3
.LBB0_776:
	s_add_u32 s26, s22, 0xfffc0080
	s_addc_u32 s27, s23, -1
	s_add_i32 s36, 0, 0x10000
	s_cmp_eq_u32 s55, 12
	s_cselect_b32 s31, s15, s27
	s_cselect_b32 s30, s51, s26
	s_cselect_b32 s27, s13, s54
	s_cselect_b32 s26, s52, s53
	s_add_i32 s56, 0, 0x14000
	v_add_u32_e32 v140, s36, v204
	v_add_u32_e32 v156, s56, v204
	ds_read_b128 v[128:131], v140
	ds_read_b128 v[132:135], v140 offset:1024
	ds_read_b128 v[136:139], v140 offset:2048
	ds_read_b128 v[140:143], v140 offset:3072
	ds_read_b128 v[144:147], v156
	ds_read_b128 v[148:151], v156 offset:1024
	ds_read_b128 v[152:155], v156 offset:2048
	ds_read_b128 v[156:159], v156 offset:3072
	s_add_i32 m0, s42, 0xc000
	ds_read_b128 v[182:185], v206
	ds_read_b128 v[186:189], v206 offset:1024
	ds_read_b128 v[190:193], v206 offset:2048
	ds_read_b128 v[194:197], v206 offset:3072
	ds_read_b128 v[198:201], v206 offset:4096
	ds_read_b128 v[208:211], v206 offset:5120
	ds_read_b128 v[212:215], v206 offset:6144
	ds_read_b128 v[228:231], v206 offset:7168
	global_load_lds_dwordx4 v166, s[22:23]
	s_add_i32 m0, s42, 0xe000
	s_nop 0
	global_load_lds_dwordx4 v180, s[22:23]
	s_cmp_eq_u32 vcc_lo, 1
	s_cbranch_scc1 .Ltw_776_0
	s_waitcnt vmcnt(8)
.Ltw_776_0:
	s_waitcnt vmcnt(32)
	s_waitcnt lgkmcnt(0)
	s_barrier
	v_mfma_f32_16x16x32_bf16 v[124:127], v[128:131], v[182:185], v[124:127]
	v_mfma_f32_16x16x32_bf16 v[124:127], v[132:135], v[186:189], v[124:127]
	v_mfma_f32_16x16x32_bf16 v[120:123], v[140:143], v[186:189], v[120:123]
	v_mfma_f32_16x16x32_bf16 v[120:123], v[136:139], v[182:185], v[120:123]
	v_mfma_f32_16x16x32_bf16 v[116:119], v[144:147], v[182:185], v[116:119]
	v_mfma_f32_16x16x32_bf16 v[116:119], v[148:151], v[186:189], v[116:119]
	v_mfma_f32_16x16x32_bf16 v[112:115], v[156:159], v[186:189], v[112:115]
	v_mfma_f32_16x16x32_bf16 v[112:115], v[152:155], v[182:185], v[112:115]
	v_mfma_f32_16x16x32_bf16 v[96:99], v[152:155], v[190:193], v[96:99]
	v_mfma_f32_16x16x32_bf16 v[96:99], v[156:159], v[194:197], v[96:99]
	v_mfma_f32_16x16x32_bf16 v[100:103], v[148:151], v[194:197], v[100:103]
	v_mfma_f32_16x16x32_bf16 v[100:103], v[144:147], v[190:193], v[100:103]
	v_mfma_f32_16x16x32_bf16 v[104:107], v[136:139], v[190:193], v[104:107]
	v_mfma_f32_16x16x32_bf16 v[104:107], v[140:143], v[194:197], v[104:107]
	v_mfma_f32_16x16x32_bf16 v[108:111], v[132:135], v[194:197], v[108:111]
	v_mfma_f32_16x16x32_bf16 v[108:111], v[128:131], v[190:193], v[108:111]
	v_mfma_f32_16x16x32_bf16 v[92:95], v[128:131], v[198:201], v[92:95]
	v_mfma_f32_16x16x32_bf16 v[92:95], v[132:135], v[208:211], v[92:95]
	v_mfma_f32_16x16x32_bf16 v[88:91], v[140:143], v[208:211], v[88:91]
	v_mfma_f32_16x16x32_bf16 v[88:91], v[136:139], v[198:201], v[88:91]
	v_mfma_f32_16x16x32_bf16 v[84:87], v[144:147], v[198:201], v[84:87]
	v_mfma_f32_16x16x32_bf16 v[84:87], v[148:151], v[208:211], v[84:87]
	v_mfma_f32_16x16x32_bf16 v[80:83], v[156:159], v[208:211], v[80:83]
	v_mfma_f32_16x16x32_bf16 v[80:83], v[152:155], v[198:201], v[80:83]
	v_mfma_f32_16x16x32_bf16 v[64:67], v[152:155], v[212:215], v[64:67]
	v_mfma_f32_16x16x32_bf16 v[64:67], v[156:159], v[228:231], v[64:67]
	v_mfma_f32_16x16x32_bf16 v[68:71], v[148:151], v[228:231], v[68:71]
	v_mfma_f32_16x16x32_bf16 v[68:71], v[144:147], v[212:215], v[68:71]
	v_mfma_f32_16x16x32_bf16 v[72:75], v[136:139], v[212:215], v[72:75]
	v_mfma_f32_16x16x32_bf16 v[72:75], v[140:143], v[228:231], v[72:75]
	v_mfma_f32_16x16x32_bf16 v[76:79], v[132:135], v[228:231], v[76:79]
	v_mfma_f32_16x16x32_bf16 v[76:79], v[128:131], v[212:215], v[76:79]
	s_barrier
	s_add_i32 s36, s36, s35
	s_add_u32 s98, s26, s20
	s_addc_u32 s99, s27, s21
	s_mov_b32 m0, s36
	ds_read_b128 v[182:185], v206 offset:16384
	ds_read_b128 v[186:189], v206 offset:17408
	ds_read_b128 v[190:193], v206 offset:18432
	ds_read_b128 v[194:197], v206 offset:19456
	ds_read_b128 v[198:201], v206 offset:20480
	ds_read_b128 v[208:211], v206 offset:21504
	ds_read_b128 v[212:215], v206 offset:22528
	ds_read_b128 v[228:231], v206 offset:23552
	global_load_lds_dwordx4 v168, s[26:27]
	s_add_i32 m0, s36, 0x2000
	s_add_u32 s36, s26, 0x40000
	s_addc_u32 s37, s27, 0
	s_add_i32 s56, s56, s35
	global_load_lds_dwordx4 v160, s[26:27]
	s_mov_b32 m0, s56
	s_nop 0
	global_load_lds_dwordx4 v168, s[36:37]
	s_add_i32 m0, s56, 0x2000
	s_nop 0
	global_load_lds_dwordx4 v160, s[36:37]
	s_add_u32 s100, s30, s20
	s_addc_u32 s101, s31, s21
	s_mov_b32 m0, s42
	s_nop 0
	global_load_lds_dwordx4 v164, s[30:31]
	s_mov_b32 m0, s43
	s_nop 0
	global_load_lds_dwordx4 v162, s[30:31]
	s_cmp_eq_u32 vcc_lo, 1
	s_cbranch_scc1 .Ltw_776_1
	s_waitcnt vmcnt(8)
.Ltw_776_1:
	s_waitcnt vmcnt(32)
	s_mov_b32 vcc_lo, 0
	s_waitcnt lgkmcnt(0)
	s_barrier
	v_mfma_f32_16x16x32_bf16 v[60:63], v[128:131], v[182:185], v[60:63]
	v_mfma_f32_16x16x32_bf16 v[60:63], v[132:135], v[186:189], v[60:63]
	v_mfma_f32_16x16x32_bf16 v[56:59], v[140:143], v[186:189], v[56:59]
	v_mfma_f32_16x16x32_bf16 v[56:59], v[136:139], v[182:185], v[56:59]
	v_mfma_f32_16x16x32_bf16 v[52:55], v[144:147], v[182:185], v[52:55]
	v_mfma_f32_16x16x32_bf16 v[52:55], v[148:151], v[186:189], v[52:55]
	v_mfma_f32_16x16x32_bf16 v[48:51], v[156:159], v[186:189], v[48:51]
	v_mfma_f32_16x16x32_bf16 v[48:51], v[152:155], v[182:185], v[48:51]
	v_mfma_f32_16x16x32_bf16 v[32:35], v[152:155], v[190:193], v[32:35]
	v_mfma_f32_16x16x32_bf16 v[32:35], v[156:159], v[194:197], v[32:35]
	v_mfma_f32_16x16x32_bf16 v[36:39], v[148:151], v[194:197], v[36:39]
	v_mfma_f32_16x16x32_bf16 v[36:39], v[144:147], v[190:193], v[36:39]
	v_mfma_f32_16x16x32_bf16 v[40:43], v[136:139], v[190:193], v[40:43]
	v_mfma_f32_16x16x32_bf16 v[40:43], v[140:143], v[194:197], v[40:43]
	v_mfma_f32_16x16x32_bf16 v[44:47], v[132:135], v[194:197], v[44:47]
	v_mfma_f32_16x16x32_bf16 v[44:47], v[128:131], v[190:193], v[44:47]
	v_mfma_f32_16x16x32_bf16 v[28:31], v[128:131], v[198:201], v[28:31]
	v_mfma_f32_16x16x32_bf16 v[28:31], v[132:135], v[208:211], v[28:31]
	v_mfma_f32_16x16x32_bf16 v[24:27], v[140:143], v[208:211], v[24:27]
	v_mfma_f32_16x16x32_bf16 v[24:27], v[136:139], v[198:201], v[24:27]
	v_mfma_f32_16x16x32_bf16 v[20:23], v[144:147], v[198:201], v[20:23]
	v_mfma_f32_16x16x32_bf16 v[20:23], v[148:151], v[208:211], v[20:23]
	v_mfma_f32_16x16x32_bf16 v[16:19], v[156:159], v[208:211], v[16:19]
	v_mfma_f32_16x16x32_bf16 v[16:19], v[152:155], v[198:201], v[16:19]
	v_mfma_f32_16x16x32_bf16 v[0:3], v[152:155], v[212:215], v[0:3]
	v_mfma_f32_16x16x32_bf16 v[0:3], v[156:159], v[228:231], v[0:3]
	v_mfma_f32_16x16x32_bf16 v[4:7], v[148:151], v[228:231], v[4:7]
	v_mfma_f32_16x16x32_bf16 v[4:7], v[144:147], v[212:215], v[4:7]
	v_mfma_f32_16x16x32_bf16 v[8:11], v[136:139], v[212:215], v[8:11]
	v_mfma_f32_16x16x32_bf16 v[8:11], v[140:143], v[228:231], v[8:11]
	v_mfma_f32_16x16x32_bf16 v[12:15], v[132:135], v[228:231], v[12:15]
	v_mfma_f32_16x16x32_bf16 v[12:15], v[128:131], v[212:215], v[12:15]
	s_barrier
	s_add_i32 s36, 0, 0x18000
	s_add_i32 s37, 0, 0x1c000
	v_add_u32_e32 v140, s36, v204
	v_add_u32_e32 v156, s37, v204
	ds_read_b128 v[128:131], v140
	ds_read_b128 v[132:135], v140 offset:1024
	ds_read_b128 v[136:139], v140 offset:2048
	ds_read_b128 v[140:143], v140 offset:3072
	ds_read_b128 v[144:147], v156
	ds_read_b128 v[148:151], v156 offset:1024
	ds_read_b128 v[152:155], v156 offset:2048
	ds_read_b128 v[156:159], v156 offset:3072
	s_add_u32 s30, s30, 0x40000
	s_addc_u32 s31, s31, 0
	s_mov_b32 m0, s44
	ds_read_b128 v[182:185], v206 offset:32768
	ds_read_b128 v[186:189], v206 offset:33792
	ds_read_b128 v[190:193], v206 offset:34816
	ds_read_b128 v[194:197], v206 offset:35840
	ds_read_b128 v[198:201], v206 offset:36864
	ds_read_b128 v[208:211], v206 offset:37888
	ds_read_b128 v[212:215], v206 offset:38912
	ds_read_b128 v[228:231], v206 offset:39936
	global_load_lds_dwordx4 v164, s[30:31]
	s_mov_b32 m0, s45
	s_nop 0
	global_load_lds_dwordx4 v162, s[30:31]
	s_waitcnt vmcnt(8)
	s_waitcnt lgkmcnt(0)
	s_barrier
	v_mfma_f32_16x16x32_bf16 v[124:127], v[128:131], v[182:185], v[124:127]
	v_mfma_f32_16x16x32_bf16 v[124:127], v[132:135], v[186:189], v[124:127]
	v_mfma_f32_16x16x32_bf16 v[120:123], v[140:143], v[186:189], v[120:123]
	v_mfma_f32_16x16x32_bf16 v[120:123], v[136:139], v[182:185], v[120:123]
	v_mfma_f32_16x16x32_bf16 v[116:119], v[144:147], v[182:185], v[116:119]
	v_mfma_f32_16x16x32_bf16 v[116:119], v[148:151], v[186:189], v[116:119]
	v_mfma_f32_16x16x32_bf16 v[112:115], v[156:159], v[186:189], v[112:115]
	v_mfma_f32_16x16x32_bf16 v[112:115], v[152:155], v[182:185], v[112:115]
	v_mfma_f32_16x16x32_bf16 v[96:99], v[152:155], v[190:193], v[96:99]
	v_mfma_f32_16x16x32_bf16 v[96:99], v[156:159], v[194:197], v[96:99]
	v_mfma_f32_16x16x32_bf16 v[100:103], v[148:151], v[194:197], v[100:103]
	v_mfma_f32_16x16x32_bf16 v[100:103], v[144:147], v[190:193], v[100:103]
	v_mfma_f32_16x16x32_bf16 v[104:107], v[136:139], v[190:193], v[104:107]
	v_mfma_f32_16x16x32_bf16 v[104:107], v[140:143], v[194:197], v[104:107]
	v_mfma_f32_16x16x32_bf16 v[108:111], v[132:135], v[194:197], v[108:111]
	v_mfma_f32_16x16x32_bf16 v[108:111], v[128:131], v[190:193], v[108:111]
	v_mfma_f32_16x16x32_bf16 v[92:95], v[128:131], v[198:201], v[92:95]
	v_mfma_f32_16x16x32_bf16 v[92:95], v[132:135], v[208:211], v[92:95]
	v_mfma_f32_16x16x32_bf16 v[88:91], v[140:143], v[208:211], v[88:91]
	v_mfma_f32_16x16x32_bf16 v[88:91], v[136:139], v[198:201], v[88:91]
	v_mfma_f32_16x16x32_bf16 v[84:87], v[144:147], v[198:201], v[84:87]
	v_mfma_f32_16x16x32_bf16 v[84:87], v[148:151], v[208:211], v[84:87]
	v_mfma_f32_16x16x32_bf16 v[80:83], v[156:159], v[208:211], v[80:83]
	v_mfma_f32_16x16x32_bf16 v[80:83], v[152:155], v[198:201], v[80:83]
	v_mfma_f32_16x16x32_bf16 v[64:67], v[152:155], v[212:215], v[64:67]
	v_mfma_f32_16x16x32_bf16 v[64:67], v[156:159], v[228:231], v[64:67]
	v_mfma_f32_16x16x32_bf16 v[68:71], v[148:151], v[228:231], v[68:71]
	v_mfma_f32_16x16x32_bf16 v[68:71], v[144:147], v[212:215], v[68:71]
	v_mfma_f32_16x16x32_bf16 v[72:75], v[136:139], v[212:215], v[72:75]
	v_mfma_f32_16x16x32_bf16 v[72:75], v[140:143], v[228:231], v[72:75]
	v_mfma_f32_16x16x32_bf16 v[76:79], v[132:135], v[228:231], v[76:79]
	v_mfma_f32_16x16x32_bf16 v[76:79], v[128:131], v[212:215], v[76:79]
	s_barrier
	s_add_i32 s30, s36, s35
	s_mov_b32 m0, s30
	ds_read_b128 v[182:185], v206 offset:49152
	ds_read_b128 v[186:189], v206 offset:50176
	ds_read_b128 v[190:193], v206 offset:51200
	ds_read_b128 v[194:197], v206 offset:52224
	ds_read_b128 v[198:201], v206 offset:53248
	ds_read_b128 v[208:211], v206 offset:54272
	ds_read_b128 v[212:215], v206 offset:55296
	ds_read_b128 v[228:231], v206 offset:56320
	global_load_lds_dwordx4 v168, s[98:99]
	s_add_i32 m0, s30, 0x2000
	s_add_u32 s26, s26, 0x40080
	s_addc_u32 s27, s27, 0
	s_add_i32 s30, s37, s35
	global_load_lds_dwordx4 v160, s[98:99]
	s_mov_b32 m0, s30
	s_nop 0
	global_load_lds_dwordx4 v168, s[26:27]
	s_add_i32 m0, s30, 0x2000
	s_nop 0
	global_load_lds_dwordx4 v160, s[26:27]
	s_mov_b32 m0, s47
	s_nop 0
	global_load_lds_dwordx4 v164, s[100:101]
	s_mov_b32 m0, s48
	s_nop 0
	global_load_lds_dwordx4 v162, s[100:101]
	s_waitcnt vmcnt(8)
	s_waitcnt lgkmcnt(0)
	s_barrier
	v_mfma_f32_16x16x32_bf16 v[60:63], v[128:131], v[182:185], v[60:63]
	v_mfma_f32_16x16x32_bf16 v[60:63], v[132:135], v[186:189], v[60:63]
	v_mfma_f32_16x16x32_bf16 v[56:59], v[140:143], v[186:189], v[56:59]
	v_mfma_f32_16x16x32_bf16 v[56:59], v[136:139], v[182:185], v[56:59]
	v_mfma_f32_16x16x32_bf16 v[52:55], v[144:147], v[182:185], v[52:55]
	v_mfma_f32_16x16x32_bf16 v[52:55], v[148:151], v[186:189], v[52:55]
	v_mfma_f32_16x16x32_bf16 v[48:51], v[156:159], v[186:189], v[48:51]
	v_mfma_f32_16x16x32_bf16 v[48:51], v[152:155], v[182:185], v[48:51]
	v_mfma_f32_16x16x32_bf16 v[32:35], v[152:155], v[190:193], v[32:35]
	v_mfma_f32_16x16x32_bf16 v[32:35], v[156:159], v[194:197], v[32:35]
	v_mfma_f32_16x16x32_bf16 v[36:39], v[148:151], v[194:197], v[36:39]
	v_mfma_f32_16x16x32_bf16 v[36:39], v[144:147], v[190:193], v[36:39]
	v_mfma_f32_16x16x32_bf16 v[40:43], v[136:139], v[190:193], v[40:43]
	v_mfma_f32_16x16x32_bf16 v[40:43], v[140:143], v[194:197], v[40:43]
	v_mfma_f32_16x16x32_bf16 v[44:47], v[132:135], v[194:197], v[44:47]
	v_mfma_f32_16x16x32_bf16 v[44:47], v[128:131], v[190:193], v[44:47]
	v_mfma_f32_16x16x32_bf16 v[28:31], v[128:131], v[198:201], v[28:31]
	v_mfma_f32_16x16x32_bf16 v[28:31], v[132:135], v[208:211], v[28:31]
	v_mfma_f32_16x16x32_bf16 v[24:27], v[140:143], v[208:211], v[24:27]
	v_mfma_f32_16x16x32_bf16 v[24:27], v[136:139], v[198:201], v[24:27]
	v_mfma_f32_16x16x32_bf16 v[20:23], v[144:147], v[198:201], v[20:23]
	v_mfma_f32_16x16x32_bf16 v[20:23], v[148:151], v[208:211], v[20:23]
	v_mfma_f32_16x16x32_bf16 v[16:19], v[156:159], v[208:211], v[16:19]
	v_mfma_f32_16x16x32_bf16 v[16:19], v[152:155], v[198:201], v[16:19]
	v_mfma_f32_16x16x32_bf16 v[0:3], v[152:155], v[212:215], v[0:3]
	v_mfma_f32_16x16x32_bf16 v[0:3], v[156:159], v[228:231], v[0:3]
	v_mfma_f32_16x16x32_bf16 v[4:7], v[148:151], v[228:231], v[4:7]
	v_mfma_f32_16x16x32_bf16 v[4:7], v[144:147], v[212:215], v[4:7]
	v_mfma_f32_16x16x32_bf16 v[8:11], v[136:139], v[212:215], v[8:11]
	v_mfma_f32_16x16x32_bf16 v[8:11], v[140:143], v[228:231], v[8:11]
	v_mfma_f32_16x16x32_bf16 v[12:15], v[132:135], v[228:231], v[12:15]
	v_mfma_f32_16x16x32_bf16 v[12:15], v[128:131], v[212:215], v[12:15]
	s_barrier
	s_add_i32 s55, s55, 2
	s_add_u32 s22, s22, 0x100
	s_addc_u32 s23, s23, 0
	s_add_u32 s53, s53, 0x100
	s_addc_u32 s54, s54, 0
	s_cmp_gt_u32 s55, 13
	s_cbranch_scc0 .LBB0_776
	s_mov_b32 vcc_lo, 1
	v_writelane_b32 v251, vcc_lo, 3
	s_and_b64 vcc, exec, s[10:11]
	s_cbranch_vccz .LBB0_779
	s_barrier

.LBB0_874:
	s_mov_b32 vcc_lo, 0
	v_writelane_b32 v251, vcc_lo, 3
	v_readlane_b32 s2, v250, 22
	v_readlane_b32 s3, v250, 23
	s_cmp_le_i32 s2, s5
	s_cselect_b64 s[0:1], -1, 0
	s_cmp_lt_i32 s5, s3
	s_cselect_b64 s[2:3], -1, 0
	s_and_b64 s[2:3], s[0:1], s[2:3]
	s_mov_b64 s[0:1], -1
	s_and_b64 vcc, exec, s[2:3]
	s_cbranch_vccnz .LBB0_876
	v_readlane_b32 s0, v246, 31
	s_add_i32 s5, s0, 7
	s_mov_b64 s[0:1], 0

.LBB0_889:
	s_ashr_i32 s13, s12, 31
	s_lshl_b64 s[14:15], s[12:13], 19
	v_readlane_b32 s16, v247, 5
	v_readlane_b32 s17, v247, 6
	s_add_u32 s14, s16, s14
	s_addc_u32 s15, s17, s15
	s_and_b64 s[16:17], s[6:7], exec
	s_cselect_b32 s13, s15, s1
	s_cselect_b32 s46, s14, s0
	s_ashr_i32 s11, s10, 31
	s_lshl_b64 s[16:17], s[10:11], 19
	s_add_u32 s16, s5, s16
	s_addc_u32 s17, s26, s17
	s_and_b64 s[22:23], s[6:7], exec
	s_cselect_b32 s11, s17, s19
	s_cselect_b32 s47, s16, s18
	s_add_u32 s0, s0, 0x40080
	s_addc_u32 s1, s1, 0
	s_add_u32 s48, s18, 0x100
	v_mov_b32_e32 v0, 0
	s_addc_u32 s49, s19, 0
	s_mov_b32 s50, -2
	v_mov_b32_e32 v1, v0
	v_mov_b32_e32 v2, v0
	v_mov_b32_e32 v3, v0
	v_mov_b32_e32 v4, v0
	v_mov_b32_e32 v5, v0
	v_mov_b32_e32 v6, v0
	v_mov_b32_e32 v7, v0
	v_mov_b32_e32 v16, v0
	v_mov_b32_e32 v17, v0
	v_mov_b32_e32 v18, v0
	v_mov_b32_e32 v19, v0
	v_mov_b32_e32 v20, v0
	v_mov_b32_e32 v21, v0
	v_mov_b32_e32 v22, v0
	v_mov_b32_e32 v23, v0
	v_mov_b32_e32 v32, v0
	v_mov_b32_e32 v33, v0
	v_mov_b32_e32 v34, v0
	v_mov_b32_e32 v35, v0
	v_mov_b32_e32 v36, v0
	v_mov_b32_e32 v37, v0
	v_mov_b32_e32 v38, v0
	v_mov_b32_e32 v39, v0
	v_mov_b32_e32 v48, v0
	v_mov_b32_e32 v49, v0
	v_mov_b32_e32 v50, v0
	v_mov_b32_e32 v51, v0
	v_mov_b32_e32 v52, v0
	v_mov_b32_e32 v53, v0
	v_mov_b32_e32 v54, v0
	v_mov_b32_e32 v55, v0
	v_mov_b32_e32 v8, v0
	v_mov_b32_e32 v9, v0
	v_mov_b32_e32 v10, v0
	v_mov_b32_e32 v11, v0
	v_mov_b32_e32 v12, v0
	v_mov_b32_e32 v13, v0
	v_mov_b32_e32 v14, v0
	v_mov_b32_e32 v15, v0
	v_mov_b32_e32 v24, v0
	v_mov_b32_e32 v25, v0
	v_mov_b32_e32 v26, v0
	v_mov_b32_e32 v27, v0
	v_mov_b32_e32 v28, v0
	v_mov_b32_e32 v29, v0
	v_mov_b32_e32 v30, v0
	v_mov_b32_e32 v31, v0
	v_mov_b32_e32 v40, v0
	v_mov_b32_e32 v41, v0
	v_mov_b32_e32 v42, v0
	v_mov_b32_e32 v43, v0
	v_mov_b32_e32 v44, v0
	v_mov_b32_e32 v45, v0
	v_mov_b32_e32 v46, v0
	v_mov_b32_e32 v47, v0
	v_mov_b32_e32 v56, v0
	v_mov_b32_e32 v57, v0
	v_mov_b32_e32 v58, v0
	v_mov_b32_e32 v59, v0
	v_mov_b32_e32 v60, v0
	v_mov_b32_e32 v61, v0
	v_mov_b32_e32 v62, v0
	v_mov_b32_e32 v63, v0
	v_mov_b32_e32 v64, v0
	v_mov_b32_e32 v65, v0
	v_mov_b32_e32 v66, v0
	v_mov_b32_e32 v67, v0
	v_mov_b32_e32 v68, v0
	v_mov_b32_e32 v69, v0
	v_mov_b32_e32 v70, v0
	v_mov_b32_e32 v71, v0
	v_mov_b32_e32 v80, v0
	v_mov_b32_e32 v81, v0
	v_mov_b32_e32 v82, v0
	v_mov_b32_e32 v83, v0
	v_mov_b32_e32 v84, v0
	v_mov_b32_e32 v85, v0
	v_mov_b32_e32 v86, v0
	v_mov_b32_e32 v87, v0
	v_mov_b32_e32 v96, v0
	v_mov_b32_e32 v97, v0
	v_mov_b32_e32 v98, v0
	v_mov_b32_e32 v99, v0
	v_mov_b32_e32 v100, v0
	v_mov_b32_e32 v101, v0
	v_mov_b32_e32 v102, v0
	v_mov_b32_e32 v103, v0
	v_mov_b32_e32 v112, v0
	v_mov_b32_e32 v113, v0
	v_mov_b32_e32 v114, v0
	v_mov_b32_e32 v115, v0
	v_mov_b32_e32 v116, v0
	v_mov_b32_e32 v117, v0
	v_mov_b32_e32 v118, v0
	v_mov_b32_e32 v119, v0
	v_mov_b32_e32 v72, v0
	v_mov_b32_e32 v73, v0
	v_mov_b32_e32 v74, v0
	v_mov_b32_e32 v75, v0
	v_mov_b32_e32 v76, v0
	v_mov_b32_e32 v77, v0
	v_mov_b32_e32 v78, v0
	v_mov_b32_e32 v79, v0
	v_mov_b32_e32 v88, v0
	v_mov_b32_e32 v89, v0
	v_mov_b32_e32 v90, v0
	v_mov_b32_e32 v91, v0
	v_mov_b32_e32 v92, v0
	v_mov_b32_e32 v93, v0
	v_mov_b32_e32 v94, v0
	v_mov_b32_e32 v95, v0
	v_mov_b32_e32 v104, v0
	v_mov_b32_e32 v105, v0
	v_mov_b32_e32 v106, v0
	v_mov_b32_e32 v107, v0
	v_mov_b32_e32 v108, v0
	v_mov_b32_e32 v109, v0
	v_mov_b32_e32 v110, v0
	v_mov_b32_e32 v111, v0
	v_mov_b32_e32 v120, v0
	v_mov_b32_e32 v121, v0
	v_mov_b32_e32 v122, v0
	v_mov_b32_e32 v123, v0
	v_mov_b32_e32 v124, v0
	v_mov_b32_e32 v125, v0
	v_mov_b32_e32 v126, v0
	v_mov_b32_e32 v127, v0
	v_readlane_b32 vcc_lo, v251, 3
	s_nop 3
.LBB0_890:
	s_add_u32 s18, s0, 0xfffc0080
	s_addc_u32 s19, s1, -1
	s_add_i32 s36, 0, 0x10000
	s_cmp_eq_u32 s50, 12
	s_cselect_b32 s23, s13, s19
	s_cselect_b32 s22, s46, s18
	s_cselect_b32 s19, s11, s49
	s_cselect_b32 s18, s47, s48
	s_add_i32 s51, 0, 0x14000
	v_add_u32_e32 v140, s36, v193
	v_add_u32_e32 v180, s51, v193
	ds_read_b128 v[128:131], v140
	ds_read_b128 v[132:135], v140 offset:1024
	ds_read_b128 v[136:139], v140 offset:2048
	ds_read_b128 v[140:143], v140 offset:3072
	ds_read_b128 v[144:147], v180
	ds_read_b128 v[148:151], v180 offset:1024
	ds_read_b128 v[164:167], v180 offset:2048
	ds_read_b128 v[180:183], v180 offset:3072
	s_add_i32 m0, s30, 0xc000
	ds_read_b128 v[184:187], v198
	ds_read_b128 v[188:191], v198 offset:1024
	ds_read_b128 v[200:203], v198 offset:2048
	ds_read_b128 v[204:207], v198 offset:3072
	ds_read_b128 v[208:211], v198 offset:4096
	ds_read_b128 v[212:215], v198 offset:5120
	ds_read_b128 v[228:231], v198 offset:6144
	ds_read_b128 v[232:235], v198 offset:7168
	global_load_lds_dwordx4 v160, s[0:1]
	s_add_i32 m0, s30, 0xe000
	s_nop 0
	global_load_lds_dwordx4 v162, s[0:1]
	s_cmp_eq_u32 vcc_lo, 1
	s_cbranch_scc1 .Ltw_890_0
	s_waitcnt vmcnt(8)
.Ltw_890_0:
	s_waitcnt vmcnt(32)
	s_waitcnt lgkmcnt(0)
	s_barrier
	v_mfma_f32_16x16x32_bf16 v[124:127], v[128:131], v[184:187], v[124:127]
	v_mfma_f32_16x16x32_bf16 v[124:127], v[132:135], v[188:191], v[124:127]
	v_mfma_f32_16x16x32_bf16 v[120:123], v[140:143], v[188:191], v[120:123]
	v_mfma_f32_16x16x32_bf16 v[120:123], v[136:139], v[184:187], v[120:123]
	v_mfma_f32_16x16x32_bf16 v[116:119], v[144:147], v[184:187], v[116:119]
	v_mfma_f32_16x16x32_bf16 v[116:119], v[148:151], v[188:191], v[116:119]
	v_mfma_f32_16x16x32_bf16 v[112:115], v[180:183], v[188:191], v[112:115]
	v_mfma_f32_16x16x32_bf16 v[112:115], v[164:167], v[184:187], v[112:115]
	v_mfma_f32_16x16x32_bf16 v[96:99], v[164:167], v[200:203], v[96:99]
	v_mfma_f32_16x16x32_bf16 v[96:99], v[180:183], v[204:207], v[96:99]
	v_mfma_f32_16x16x32_bf16 v[100:103], v[148:151], v[204:207], v[100:103]
	v_mfma_f32_16x16x32_bf16 v[100:103], v[144:147], v[200:203], v[100:103]
	v_mfma_f32_16x16x32_bf16 v[104:107], v[136:139], v[200:203], v[104:107]
	v_mfma_f32_16x16x32_bf16 v[104:107], v[140:143], v[204:207], v[104:107]
	v_mfma_f32_16x16x32_bf16 v[108:111], v[132:135], v[204:207], v[108:111]
	v_mfma_f32_16x16x32_bf16 v[108:111], v[128:131], v[200:203], v[108:111]
	v_mfma_f32_16x16x32_bf16 v[92:95], v[128:131], v[208:211], v[92:95]
	v_mfma_f32_16x16x32_bf16 v[92:95], v[132:135], v[212:215], v[92:95]
	v_mfma_f32_16x16x32_bf16 v[88:91], v[140:143], v[212:215], v[88:91]
	v_mfma_f32_16x16x32_bf16 v[88:91], v[136:139], v[208:211], v[88:91]
	v_mfma_f32_16x16x32_bf16 v[84:87], v[144:147], v[208:211], v[84:87]
	v_mfma_f32_16x16x32_bf16 v[84:87], v[148:151], v[212:215], v[84:87]
	v_mfma_f32_16x16x32_bf16 v[80:83], v[180:183], v[212:215], v[80:83]
	v_mfma_f32_16x16x32_bf16 v[80:83], v[164:167], v[208:211], v[80:83]
	v_mfma_f32_16x16x32_bf16 v[64:67], v[164:167], v[228:231], v[64:67]
	v_mfma_f32_16x16x32_bf16 v[64:67], v[180:183], v[232:235], v[64:67]
	v_mfma_f32_16x16x32_bf16 v[68:71], v[148:151], v[232:235], v[68:71]
	v_mfma_f32_16x16x32_bf16 v[68:71], v[144:147], v[228:231], v[68:71]
	v_mfma_f32_16x16x32_bf16 v[72:75], v[136:139], v[228:231], v[72:75]
	v_mfma_f32_16x16x32_bf16 v[72:75], v[140:143], v[232:235], v[72:75]
	v_mfma_f32_16x16x32_bf16 v[76:79], v[132:135], v[232:235], v[76:79]
	v_mfma_f32_16x16x32_bf16 v[76:79], v[128:131], v[228:231], v[76:79]
	s_barrier
	s_add_i32 s36, s36, s27
	s_add_u32 s98, s18, s20
	s_addc_u32 s99, s19, s21
	s_mov_b32 m0, s36
	ds_read_b128 v[184:187], v198 offset:16384
	ds_read_b128 v[188:191], v198 offset:17408
	ds_read_b128 v[200:203], v198 offset:18432
	ds_read_b128 v[204:207], v198 offset:19456
	ds_read_b128 v[208:211], v198 offset:20480
	ds_read_b128 v[212:215], v198 offset:21504
	ds_read_b128 v[228:231], v198 offset:22528
	ds_read_b128 v[232:235], v198 offset:23552
	global_load_lds_dwordx4 v168, s[18:19]
	s_add_i32 m0, s36, 0x2000
	s_add_u32 s36, s18, 0x40000
	s_addc_u32 s37, s19, 0
	s_add_i32 s51, s51, s27
	global_load_lds_dwordx4 v152, s[18:19]
	s_mov_b32 m0, s51
	s_nop 0
	global_load_lds_dwordx4 v168, s[36:37]
	s_add_i32 m0, s51, 0x2000
	s_nop 0
	global_load_lds_dwordx4 v152, s[36:37]
	s_add_u32 s100, s22, s20
	s_addc_u32 s101, s23, s21
	s_mov_b32 m0, s30
	s_nop 0
	global_load_lds_dwordx4 v156, s[22:23]
	s_mov_b32 m0, s31
	s_nop 0
	global_load_lds_dwordx4 v154, s[22:23]
	s_cmp_eq_u32 vcc_lo, 1
	s_cbranch_scc1 .Ltw_890_1
	s_waitcnt vmcnt(8)
.Ltw_890_1:
	s_waitcnt vmcnt(32)
	s_mov_b32 vcc_lo, 0
	s_waitcnt lgkmcnt(0)
	s_barrier
	v_mfma_f32_16x16x32_bf16 v[60:63], v[128:131], v[184:187], v[60:63]
	v_mfma_f32_16x16x32_bf16 v[60:63], v[132:135], v[188:191], v[60:63]
	v_mfma_f32_16x16x32_bf16 v[56:59], v[140:143], v[188:191], v[56:59]
	v_mfma_f32_16x16x32_bf16 v[56:59], v[136:139], v[184:187], v[56:59]
	v_mfma_f32_16x16x32_bf16 v[52:55], v[144:147], v[184:187], v[52:55]
	v_mfma_f32_16x16x32_bf16 v[52:55], v[148:151], v[188:191], v[52:55]
	v_mfma_f32_16x16x32_bf16 v[48:51], v[180:183], v[188:191], v[48:51]
	v_mfma_f32_16x16x32_bf16 v[48:51], v[164:167], v[184:187], v[48:51]
	v_mfma_f32_16x16x32_bf16 v[32:35], v[164:167], v[200:203], v[32:35]
	v_mfma_f32_16x16x32_bf16 v[32:35], v[180:183], v[204:207], v[32:35]
	v_mfma_f32_16x16x32_bf16 v[36:39], v[148:151], v[204:207], v[36:39]
	v_mfma_f32_16x16x32_bf16 v[36:39], v[144:147], v[200:203], v[36:39]
	v_mfma_f32_16x16x32_bf16 v[40:43], v[136:139], v[200:203], v[40:43]
	v_mfma_f32_16x16x32_bf16 v[40:43], v[140:143], v[204:207], v[40:43]
	v_mfma_f32_16x16x32_bf16 v[44:47], v[132:135], v[204:207], v[44:47]
	v_mfma_f32_16x16x32_bf16 v[44:47], v[128:131], v[200:203], v[44:47]
	v_mfma_f32_16x16x32_bf16 v[28:31], v[128:131], v[208:211], v[28:31]
	v_mfma_f32_16x16x32_bf16 v[28:31], v[132:135], v[212:215], v[28:31]
	v_mfma_f32_16x16x32_bf16 v[24:27], v[140:143], v[212:215], v[24:27]
	v_mfma_f32_16x16x32_bf16 v[24:27], v[136:139], v[208:211], v[24:27]
	v_mfma_f32_16x16x32_bf16 v[20:23], v[144:147], v[208:211], v[20:23]
	v_mfma_f32_16x16x32_bf16 v[20:23], v[148:151], v[212:215], v[20:23]
	v_mfma_f32_16x16x32_bf16 v[16:19], v[180:183], v[212:215], v[16:19]
	v_mfma_f32_16x16x32_bf16 v[16:19], v[164:167], v[208:211], v[16:19]
	v_mfma_f32_16x16x32_bf16 v[0:3], v[164:167], v[228:231], v[0:3]
	v_mfma_f32_16x16x32_bf16 v[0:3], v[180:183], v[232:235], v[0:3]
	v_mfma_f32_16x16x32_bf16 v[4:7], v[148:151], v[232:235], v[4:7]
	v_mfma_f32_16x16x32_bf16 v[4:7], v[144:147], v[228:231], v[4:7]
	v_mfma_f32_16x16x32_bf16 v[8:11], v[136:139], v[228:231], v[8:11]
	v_mfma_f32_16x16x32_bf16 v[8:11], v[140:143], v[232:235], v[8:11]
	v_mfma_f32_16x16x32_bf16 v[12:15], v[132:135], v[232:235], v[12:15]
	v_mfma_f32_16x16x32_bf16 v[12:15], v[128:131], v[228:231], v[12:15]
	s_barrier
	s_add_i32 s36, 0, 0x18000
	s_add_i32 s37, 0, 0x1c000
	v_add_u32_e32 v140, s36, v193
	v_add_u32_e32 v180, s37, v193
	ds_read_b128 v[128:131], v140
	ds_read_b128 v[132:135], v140 offset:1024
	ds_read_b128 v[136:139], v140 offset:2048
	ds_read_b128 v[140:143], v140 offset:3072
	ds_read_b128 v[144:147], v180
	ds_read_b128 v[148:151], v180 offset:1024
	ds_read_b128 v[164:167], v180 offset:2048
	ds_read_b128 v[180:183], v180 offset:3072
	s_add_u32 s22, s22, 0x40000
	s_addc_u32 s23, s23, 0
	s_mov_b32 m0, s34
	ds_read_b128 v[184:187], v198 offset:32768
	ds_read_b128 v[188:191], v198 offset:33792
	ds_read_b128 v[200:203], v198 offset:34816
	ds_read_b128 v[204:207], v198 offset:35840
	ds_read_b128 v[208:211], v198 offset:36864
	ds_read_b128 v[212:215], v198 offset:37888
	ds_read_b128 v[228:231], v198 offset:38912
	ds_read_b128 v[232:235], v198 offset:39936
	global_load_lds_dwordx4 v156, s[22:23]
	s_mov_b32 m0, s35
	s_nop 0
	global_load_lds_dwordx4 v154, s[22:23]
	s_waitcnt vmcnt(8)
	s_waitcnt lgkmcnt(0)
	s_barrier
	v_mfma_f32_16x16x32_bf16 v[124:127], v[128:131], v[184:187], v[124:127]
	v_mfma_f32_16x16x32_bf16 v[124:127], v[132:135], v[188:191], v[124:127]
	v_mfma_f32_16x16x32_bf16 v[120:123], v[140:143], v[188:191], v[120:123]
	v_mfma_f32_16x16x32_bf16 v[120:123], v[136:139], v[184:187], v[120:123]
	v_mfma_f32_16x16x32_bf16 v[116:119], v[144:147], v[184:187], v[116:119]
	v_mfma_f32_16x16x32_bf16 v[116:119], v[148:151], v[188:191], v[116:119]
	v_mfma_f32_16x16x32_bf16 v[112:115], v[180:183], v[188:191], v[112:115]
	v_mfma_f32_16x16x32_bf16 v[112:115], v[164:167], v[184:187], v[112:115]
	v_mfma_f32_16x16x32_bf16 v[96:99], v[164:167], v[200:203], v[96:99]
	v_mfma_f32_16x16x32_bf16 v[96:99], v[180:183], v[204:207], v[96:99]
	v_mfma_f32_16x16x32_bf16 v[100:103], v[148:151], v[204:207], v[100:103]
	v_mfma_f32_16x16x32_bf16 v[100:103], v[144:147], v[200:203], v[100:103]
	v_mfma_f32_16x16x32_bf16 v[104:107], v[136:139], v[200:203], v[104:107]
	v_mfma_f32_16x16x32_bf16 v[104:107], v[140:143], v[204:207], v[104:107]
	v_mfma_f32_16x16x32_bf16 v[108:111], v[132:135], v[204:207], v[108:111]
	v_mfma_f32_16x16x32_bf16 v[108:111], v[128:131], v[200:203], v[108:111]
	v_mfma_f32_16x16x32_bf16 v[92:95], v[128:131], v[208:211], v[92:95]
	v_mfma_f32_16x16x32_bf16 v[92:95], v[132:135], v[212:215], v[92:95]
	v_mfma_f32_16x16x32_bf16 v[88:91], v[140:143], v[212:215], v[88:91]
	v_mfma_f32_16x16x32_bf16 v[88:91], v[136:139], v[208:211], v[88:91]
	v_mfma_f32_16x16x32_bf16 v[84:87], v[144:147], v[208:211], v[84:87]
	v_mfma_f32_16x16x32_bf16 v[84:87], v[148:151], v[212:215], v[84:87]
	v_mfma_f32_16x16x32_bf16 v[80:83], v[180:183], v[212:215], v[80:83]
	v_mfma_f32_16x16x32_bf16 v[80:83], v[164:167], v[208:211], v[80:83]
	v_mfma_f32_16x16x32_bf16 v[64:67], v[164:167], v[228:231], v[64:67]
	v_mfma_f32_16x16x32_bf16 v[64:67], v[180:183], v[232:235], v[64:67]
	v_mfma_f32_16x16x32_bf16 v[68:71], v[148:151], v[232:235], v[68:71]
	v_mfma_f32_16x16x32_bf16 v[68:71], v[144:147], v[228:231], v[68:71]
	v_mfma_f32_16x16x32_bf16 v[72:75], v[136:139], v[228:231], v[72:75]
	v_mfma_f32_16x16x32_bf16 v[72:75], v[140:143], v[232:235], v[72:75]
	v_mfma_f32_16x16x32_bf16 v[76:79], v[132:135], v[232:235], v[76:79]
	v_mfma_f32_16x16x32_bf16 v[76:79], v[128:131], v[228:231], v[76:79]
	s_barrier
	s_add_i32 s22, s36, s27
	s_mov_b32 m0, s22
	ds_read_b128 v[184:187], v198 offset:49152
	ds_read_b128 v[188:191], v198 offset:50176
	ds_read_b128 v[200:203], v198 offset:51200
	ds_read_b128 v[204:207], v198 offset:52224
	ds_read_b128 v[208:211], v198 offset:53248
	ds_read_b128 v[212:215], v198 offset:54272
	ds_read_b128 v[228:231], v198 offset:55296
	ds_read_b128 v[232:235], v198 offset:56320
	global_load_lds_dwordx4 v168, s[98:99]
	s_add_i32 m0, s22, 0x2000
	s_add_u32 s18, s18, 0x40080
	s_addc_u32 s19, s19, 0
	s_add_i32 s22, s37, s27
	global_load_lds_dwordx4 v152, s[98:99]
	s_mov_b32 m0, s22
	s_nop 0
	global_load_lds_dwordx4 v168, s[18:19]
	s_add_i32 m0, s22, 0x2000
	s_nop 0
	global_load_lds_dwordx4 v152, s[18:19]
	s_mov_b32 m0, s24
	s_nop 0
	global_load_lds_dwordx4 v156, s[100:101]
	s_mov_b32 m0, s42
	s_nop 0
	global_load_lds_dwordx4 v154, s[100:101]
	s_waitcnt vmcnt(8)
	s_waitcnt lgkmcnt(0)
	s_barrier
	v_mfma_f32_16x16x32_bf16 v[60:63], v[128:131], v[184:187], v[60:63]
	v_mfma_f32_16x16x32_bf16 v[60:63], v[132:135], v[188:191], v[60:63]
	v_mfma_f32_16x16x32_bf16 v[56:59], v[140:143], v[188:191], v[56:59]
	v_mfma_f32_16x16x32_bf16 v[56:59], v[136:139], v[184:187], v[56:59]
	v_mfma_f32_16x16x32_bf16 v[52:55], v[144:147], v[184:187], v[52:55]
	v_mfma_f32_16x16x32_bf16 v[52:55], v[148:151], v[188:191], v[52:55]
	v_mfma_f32_16x16x32_bf16 v[48:51], v[180:183], v[188:191], v[48:51]
	v_mfma_f32_16x16x32_bf16 v[48:51], v[164:167], v[184:187], v[48:51]
	v_mfma_f32_16x16x32_bf16 v[32:35], v[164:167], v[200:203], v[32:35]
	v_mfma_f32_16x16x32_bf16 v[32:35], v[180:183], v[204:207], v[32:35]
	v_mfma_f32_16x16x32_bf16 v[36:39], v[148:151], v[204:207], v[36:39]
	v_mfma_f32_16x16x32_bf16 v[36:39], v[144:147], v[200:203], v[36:39]
	v_mfma_f32_16x16x32_bf16 v[40:43], v[136:139], v[200:203], v[40:43]
	v_mfma_f32_16x16x32_bf16 v[40:43], v[140:143], v[204:207], v[40:43]
	v_mfma_f32_16x16x32_bf16 v[44:47], v[132:135], v[204:207], v[44:47]
	v_mfma_f32_16x16x32_bf16 v[44:47], v[128:131], v[200:203], v[44:47]
	v_mfma_f32_16x16x32_bf16 v[28:31], v[128:131], v[208:211], v[28:31]
	v_mfma_f32_16x16x32_bf16 v[28:31], v[132:135], v[212:215], v[28:31]
	v_mfma_f32_16x16x32_bf16 v[24:27], v[140:143], v[212:215], v[24:27]
	v_mfma_f32_16x16x32_bf16 v[24:27], v[136:139], v[208:211], v[24:27]
	v_mfma_f32_16x16x32_bf16 v[20:23], v[144:147], v[208:211], v[20:23]
	v_mfma_f32_16x16x32_bf16 v[20:23], v[148:151], v[212:215], v[20:23]
	v_mfma_f32_16x16x32_bf16 v[16:19], v[180:183], v[212:215], v[16:19]
	v_mfma_f32_16x16x32_bf16 v[16:19], v[164:167], v[208:211], v[16:19]
	v_mfma_f32_16x16x32_bf16 v[0:3], v[164:167], v[228:231], v[0:3]
	v_mfma_f32_16x16x32_bf16 v[0:3], v[180:183], v[232:235], v[0:3]
	v_mfma_f32_16x16x32_bf16 v[4:7], v[148:151], v[232:235], v[4:7]
	v_mfma_f32_16x16x32_bf16 v[4:7], v[144:147], v[228:231], v[4:7]
	v_mfma_f32_16x16x32_bf16 v[8:11], v[136:139], v[228:231], v[8:11]
	v_mfma_f32_16x16x32_bf16 v[8:11], v[140:143], v[232:235], v[8:11]
	v_mfma_f32_16x16x32_bf16 v[12:15], v[132:135], v[232:235], v[12:15]
	v_mfma_f32_16x16x32_bf16 v[12:15], v[128:131], v[228:231], v[12:15]
	s_barrier
	s_add_i32 s50, s50, 2
	s_add_u32 s0, s0, 0x100
	s_addc_u32 s1, s1, 0
	s_add_u32 s48, s48, 0x100
	s_addc_u32 s49, s49, 0
	s_cmp_gt_u32 s50, 13
	s_cbranch_scc0 .LBB0_890
	s_mov_b32 vcc_lo, 1
	v_writelane_b32 v251, vcc_lo, 3
	s_and_b64 vcc, exec, s[8:9]
	s_cbranch_vccz .LBB0_893
	s_barrier

.LBB0_972:
	s_mov_b32 vcc_lo, 0
	v_writelane_b32 v251, vcc_lo, 3
	v_readlane_b32 s2, v250, 22
	v_readlane_b32 s3, v250, 23
	s_cmp_le_i32 s2, s5
	s_cselect_b64 s[0:1], -1, 0
	s_cmp_lt_i32 s5, s3
	s_mov_b64 s[4:5], s[2:3]
	s_cselect_b64 s[2:3], -1, 0
	s_and_b64 s[0:1], s[0:1], s[2:3]
	s_andn2_b64 vcc, exec, s[0:1]
	s_cbranch_vccnz .LBB0_165
	s_waitcnt vmcnt(0)
	v_mov_b32_e32 v10, v216
	s_and_b64 vcc, exec, s[40:41]
	v_readfirstlane_b32 s8, v10
	s_cbranch_vccnz .LBB0_1089
	v_lshlrev_b32_e32 v0, 4, v10
	s_waitcnt lgkmcnt(0)
	v_add_u32_e32 v1, 0x2000, v0
	v_ashrrev_i32_e32 v2, 31, v1
	v_lshrrev_b32_e32 v2, 22, v2
	v_add_u32_e32 v2, v1, v2
	v_ashrrev_i32_e32 v4, 10, v2
	v_mul_i32_i24_e32 v2, 0x400, v4
	v_sub_u32_e32 v1, v1, v2
	v_lshrrev_b32_e32 v2, 4, v1
	v_bitop3_b32 v1, v2, v1, 32 bitop3:0x6c
	v_ashrrev_i32_e32 v2, 31, v1
	v_readlane_b32 s0, v246, 32
	v_lshrrev_b32_e32 v2, 26, v2
	v_readlane_b32 s1, v246, 33
	v_add_u32_e32 v2, v1, v2
	v_lshlrev_b32_e32 v3, 3, v4
	s_lshl_b32 s0, s0, 23
	v_readlane_b32 s1, v248, 56
	v_ashrrev_i32_e32 v5, 6, v2
	v_and_b32_e32 v3, -16, v3
	s_add_u32 s5, s1, s0
	v_readlane_b32 s0, v248, 57
	v_add_u32_e32 v3, v5, v3
	s_addc_u32 s42, s0, 0
	v_and_b32_e32 v6, 3, v5
	s_mov_b32 s0, 0x7ffe0
	v_lshrrev_b32_e32 v7, 2, v3
	v_lshlrev_b32_e32 v8, 1, v3
	v_and_b32_e32 v2, 0xc0, v2
	v_and_or_b32 v6, v3, s0, v6
	v_and_b32_e32 v7, 4, v7
	v_and_b32_e32 v8, 24, v8
	v_sub_u32_e32 v1, v1, v2
	v_or3_b32 v7, v6, v7, v8
	v_lshlrev_b32_e32 v6, 5, v4
	v_ashrrev_i16_sdwa v1, v217, sext(v1) dst_sel:DWORD dst_unused:UNUSED_PAD src0_sel:DWORD src1_sel:BYTE_0
	v_and_b32_e32 v8, 32, v6
	v_bfe_i32 v6, v1, 0, 16
	v_add_lshl_u32 v1, v8, v6, 1
	v_lshl_add_u32 v180, v7, 13, v1
	v_lshl_add_u32 v182, v3, 13, v1
	v_bfe_i32 v1, v10, 27, 1
	v_lshrrev_b32_e32 v1, 22, v1
	v_add_u32_e32 v1, v0, v1
	v_and_b32_e32 v1, 0xfffffc00, v1
	v_sub_u32_e32 v0, v0, v1
	v_lshrrev_b32_e32 v1, 4, v0
	v_ashrrev_i32_e32 v2, 31, v10
	v_bitop3_b32 v0, v1, v0, 32 bitop3:0x6c
	v_lshrrev_b32_e32 v2, 26, v2
	v_ashrrev_i32_e32 v1, 31, v0
	v_add_u32_e32 v2, v10, v2
	v_lshrrev_b32_e32 v1, 26, v1
	v_ashrrev_i32_e32 v8, 6, v2
	v_add_u32_e32 v1, v0, v1
	v_lshlrev_b32_e32 v2, 3, v8
	v_ashrrev_i32_e32 v7, 6, v1
	v_and_b32_e32 v2, -16, v2
	v_add_u32_e32 v2, v7, v2
	v_and_b32_e32 v3, 3, v7
	v_lshrrev_b32_e32 v9, 2, v2
	v_lshlrev_b32_e32 v11, 1, v2
	v_and_b32_e32 v1, 0xc0, v1
	s_ashr_i32 s12, s8, 6
	v_and_or_b32 v3, v2, s0, v3
	v_and_b32_e32 v9, 4, v9
	v_and_b32_e32 v11, 24, v11
	v_sub_u32_e32 v0, v0, v1
	s_ashr_i32 s9, s8, 8
	s_lshl_b32 s43, s12, 10
	v_or3_b32 v3, v3, v9, v11
	v_lshlrev_b32_e32 v9, 5, v8
	v_ashrrev_i16_sdwa v0, v217, sext(v0) dst_sel:DWORD dst_unused:UNUSED_PAD src0_sel:DWORD src1_sel:BYTE_0
	v_readlane_b32 s0, v247, 17
	v_and_b32_e32 v11, 32, v9
	v_bfe_i32 v9, v0, 0, 16
	v_readlane_b32 s1, v247, 18
	s_add_u32 s34, s5, s0
	v_add_lshl_u32 v0, v11, v9, 1
	s_addc_u32 s35, s42, s1
	s_add_i32 s44, s43, 0
	v_lshl_add_u32 v168, v3, 13, v0
	s_add_i32 m0, s44, 0x10000
	v_lshl_add_u32 v184, v2, 13, v0
	global_load_lds_dwordx4 v168, s[34:35]
	s_add_i32 m0, s44, 0x12000
	s_add_u32 s0, s34, 0x100000
	global_load_lds_dwordx4 v180, s[34:35]
	s_addc_u32 s1, s35, 0
	s_add_i32 m0, s44, 0x14000
	s_add_i32 s45, s44, 0x2000
	global_load_lds_dwordx4 v168, s[0:1]
	s_add_i32 m0, s44, 0x16000
	s_add_i32 s46, s44, 0x4000
	global_load_lds_dwordx4 v180, s[0:1]
	v_readlane_b32 s0, v247, 21
	s_mov_b32 m0, s44
	v_readlane_b32 s1, v247, 22
	s_add_i32 s47, s44, 0x6000
	v_mov_b32_e32 v181, v169
	s_cmp_eq_u32 s9, 1
	v_lshl_add_u64 v[0:1], s[34:35], 0, v[168:169]
	v_lshl_add_u64 v[2:3], s[34:35], 0, v[180:181]
	global_load_lds_dwordx4 v184, s[0:1]
	s_mov_b32 m0, s45
	s_nop 0
	global_load_lds_dwordx4 v182, s[0:1]
	v_readlane_b32 s0, v247, 23
	s_mov_b32 m0, s46
	v_readlane_b32 s1, v247, 24
	s_nop 4
	global_load_lds_dwordx4 v184, s[0:1]
	s_mov_b32 m0, s47
	s_nop 0
	global_load_lds_dwordx4 v182, s[0:1]
	s_cselect_b64 s[0:1], -1, 0
	s_cmp_lg_u32 s9, 1
	s_cbranch_scc1 .LBB0_976
	s_barrier

.LBB0_985:
	s_ashr_i32 s23, s22, 31
	s_lshl_b64 s[26:27], s[22:23], 21
	v_readlane_b32 s30, v250, 6
	v_readlane_b32 s31, v250, 7
	s_add_u32 s26, s30, s26
	s_addc_u32 s27, s31, s27
	s_and_b64 s[30:31], s[6:7], exec
	s_cselect_b32 s23, s27, s9
	s_cselect_b32 s53, s26, s8
	s_ashr_i32 s19, s18, 31
	s_lshl_b64 s[30:31], s[18:19], 21
	s_add_u32 s30, s5, s30
	s_addc_u32 s31, s42, s31
	s_and_b64 s[36:37], s[6:7], exec
	s_cselect_b32 s19, s31, s35
	s_cselect_b32 s54, s30, s34
	s_add_u32 s8, s8, 0x100080
	s_addc_u32 s9, s9, 0
	s_add_u32 s55, s34, 0x100
	v_mov_b32_e32 v0, 0
	s_addc_u32 s56, s35, 0
	s_mov_b32 s57, -2
	s_waitcnt lgkmcnt(0)
	v_mov_b32_e32 v1, v0
	v_mov_b32_e32 v2, v0
	v_mov_b32_e32 v3, v0
	v_mov_b32_e32 v4, v0
	v_mov_b32_e32 v5, v0
	v_mov_b32_e32 v6, v0
	v_mov_b32_e32 v7, v0
	v_mov_b32_e32 v16, v0
	v_mov_b32_e32 v17, v0
	v_mov_b32_e32 v18, v0
	v_mov_b32_e32 v19, v0
	v_mov_b32_e32 v20, v0
	v_mov_b32_e32 v21, v0
	v_mov_b32_e32 v22, v0
	v_mov_b32_e32 v23, v0
	v_mov_b32_e32 v32, v0
	v_mov_b32_e32 v33, v0
	v_mov_b32_e32 v34, v0
	v_mov_b32_e32 v35, v0
	v_mov_b32_e32 v36, v0
	v_mov_b32_e32 v37, v0
	v_mov_b32_e32 v38, v0
	v_mov_b32_e32 v39, v0
	v_mov_b32_e32 v48, v0
	v_mov_b32_e32 v49, v0
	v_mov_b32_e32 v50, v0
	v_mov_b32_e32 v51, v0
	v_mov_b32_e32 v52, v0
	v_mov_b32_e32 v53, v0
	v_mov_b32_e32 v54, v0
	v_mov_b32_e32 v55, v0
	v_mov_b32_e32 v8, v0
	v_mov_b32_e32 v9, v0
	v_mov_b32_e32 v10, v0
	v_mov_b32_e32 v11, v0
	v_mov_b32_e32 v12, v0
	v_mov_b32_e32 v13, v0
	v_mov_b32_e32 v14, v0
	v_mov_b32_e32 v15, v0
	v_mov_b32_e32 v24, v0
	v_mov_b32_e32 v25, v0
	v_mov_b32_e32 v26, v0
	v_mov_b32_e32 v27, v0
	v_mov_b32_e32 v28, v0
	v_mov_b32_e32 v29, v0
	v_mov_b32_e32 v30, v0
	v_mov_b32_e32 v31, v0
	v_mov_b32_e32 v40, v0
	v_mov_b32_e32 v41, v0
	v_mov_b32_e32 v42, v0
	v_mov_b32_e32 v43, v0
	v_mov_b32_e32 v44, v0
	v_mov_b32_e32 v45, v0
	v_mov_b32_e32 v46, v0
	v_mov_b32_e32 v47, v0
	v_mov_b32_e32 v56, v0
	v_mov_b32_e32 v57, v0
	v_mov_b32_e32 v58, v0
	v_mov_b32_e32 v59, v0
	v_mov_b32_e32 v60, v0
	v_mov_b32_e32 v61, v0
	v_mov_b32_e32 v62, v0
	v_mov_b32_e32 v63, v0
	v_mov_b32_e32 v64, v0
	v_mov_b32_e32 v65, v0
	v_mov_b32_e32 v66, v0
	v_mov_b32_e32 v67, v0
	v_mov_b32_e32 v68, v0
	v_mov_b32_e32 v69, v0
	v_mov_b32_e32 v70, v0
	v_mov_b32_e32 v71, v0
	v_mov_b32_e32 v80, v0
	v_mov_b32_e32 v81, v0
	v_mov_b32_e32 v82, v0
	v_mov_b32_e32 v83, v0
	v_mov_b32_e32 v84, v0
	v_mov_b32_e32 v85, v0
	v_mov_b32_e32 v86, v0
	v_mov_b32_e32 v87, v0
	v_mov_b32_e32 v96, v0
	v_mov_b32_e32 v97, v0
	v_mov_b32_e32 v98, v0
	v_mov_b32_e32 v99, v0
	v_mov_b32_e32 v100, v0
	v_mov_b32_e32 v101, v0
	v_mov_b32_e32 v102, v0
	v_mov_b32_e32 v103, v0
	v_mov_b32_e32 v112, v0
	v_mov_b32_e32 v113, v0
	v_mov_b32_e32 v114, v0
	v_mov_b32_e32 v115, v0
	v_mov_b32_e32 v116, v0
	v_mov_b32_e32 v117, v0
	v_mov_b32_e32 v118, v0
	v_mov_b32_e32 v119, v0
	v_mov_b32_e32 v72, v0
	v_mov_b32_e32 v73, v0
	v_mov_b32_e32 v74, v0
	v_mov_b32_e32 v75, v0
	v_mov_b32_e32 v76, v0
	v_mov_b32_e32 v77, v0
	v_mov_b32_e32 v78, v0
	v_mov_b32_e32 v79, v0
	v_mov_b32_e32 v88, v0
	v_mov_b32_e32 v89, v0
	v_mov_b32_e32 v90, v0
	v_mov_b32_e32 v91, v0
	v_mov_b32_e32 v92, v0
	v_mov_b32_e32 v93, v0
	v_mov_b32_e32 v94, v0
	v_mov_b32_e32 v95, v0
	v_mov_b32_e32 v104, v0
	v_mov_b32_e32 v105, v0
	v_mov_b32_e32 v106, v0
	v_mov_b32_e32 v107, v0
	v_mov_b32_e32 v108, v0
	v_mov_b32_e32 v109, v0
	v_mov_b32_e32 v110, v0
	v_mov_b32_e32 v111, v0
	v_mov_b32_e32 v120, v0
	v_mov_b32_e32 v121, v0
	v_mov_b32_e32 v122, v0
	v_mov_b32_e32 v123, v0
	v_mov_b32_e32 v124, v0
	v_mov_b32_e32 v125, v0
	v_mov_b32_e32 v126, v0
	v_mov_b32_e32 v127, v0
	v_readlane_b32 vcc_lo, v251, 3
	s_nop 3
.LBB0_986:
	s_add_u32 s34, s8, 0xfff00080
	s_addc_u32 s35, s9, -1
	s_add_i32 s36, 0, 0x10000
	s_cmp_eq_u32 s57, 60
	s_cselect_b32 s41, s23, s35
	s_cselect_b32 s40, s53, s34
	s_cselect_b32 s35, s19, s56
	s_cselect_b32 s34, s54, s55
	s_add_i32 s58, 0, 0x14000
	v_add_u32_e32 v140, s36, v228
	v_add_u32_e32 v156, s58, v228
	ds_read_b128 v[128:131], v140
	ds_read_b128 v[132:135], v140 offset:1024
	ds_read_b128 v[136:139], v140 offset:2048
	ds_read_b128 v[140:143], v140 offset:3072
	ds_read_b128 v[144:147], v156
	ds_read_b128 v[148:151], v156 offset:1024
	ds_read_b128 v[152:155], v156 offset:2048
	ds_read_b128 v[156:159], v156 offset:3072
	s_add_i32 m0, s44, 0xc000
	ds_read_b128 v[160:163], v230
	ds_read_b128 v[164:167], v230 offset:1024
	ds_read_b128 v[190:193], v230 offset:2048
	ds_read_b128 v[194:197], v230 offset:3072
	ds_read_b128 v[198:201], v230 offset:4096
	ds_read_b128 v[202:205], v230 offset:5120
	ds_read_b128 v[206:209], v230 offset:6144
	ds_read_b128 v[210:213], v230 offset:7168
	global_load_lds_dwordx4 v186, s[8:9]
	s_add_i32 m0, s44, 0xe000
	s_nop 0
	global_load_lds_dwordx4 v188, s[8:9]
	s_cmp_eq_u32 vcc_lo, 1
	s_cbranch_scc1 .Ltw_986_0
	s_waitcnt vmcnt(8)
.Ltw_986_0:
	s_waitcnt vmcnt(32)
	s_waitcnt lgkmcnt(0)
	s_barrier
	v_mfma_f32_16x16x32_bf16 v[124:127], v[128:131], v[160:163], v[124:127]
	v_mfma_f32_16x16x32_bf16 v[124:127], v[132:135], v[164:167], v[124:127]
	v_mfma_f32_16x16x32_bf16 v[120:123], v[140:143], v[164:167], v[120:123]
	v_mfma_f32_16x16x32_bf16 v[120:123], v[136:139], v[160:163], v[120:123]
	v_mfma_f32_16x16x32_bf16 v[116:119], v[144:147], v[160:163], v[116:119]
	v_mfma_f32_16x16x32_bf16 v[116:119], v[148:151], v[164:167], v[116:119]
	v_mfma_f32_16x16x32_bf16 v[112:115], v[156:159], v[164:167], v[112:115]
	v_mfma_f32_16x16x32_bf16 v[112:115], v[152:155], v[160:163], v[112:115]
	v_mfma_f32_16x16x32_bf16 v[96:99], v[152:155], v[190:193], v[96:99]
	v_mfma_f32_16x16x32_bf16 v[96:99], v[156:159], v[194:197], v[96:99]
	v_mfma_f32_16x16x32_bf16 v[100:103], v[148:151], v[194:197], v[100:103]
	v_mfma_f32_16x16x32_bf16 v[100:103], v[144:147], v[190:193], v[100:103]
	v_mfma_f32_16x16x32_bf16 v[104:107], v[136:139], v[190:193], v[104:107]
	v_mfma_f32_16x16x32_bf16 v[104:107], v[140:143], v[194:197], v[104:107]
	v_mfma_f32_16x16x32_bf16 v[108:111], v[132:135], v[194:197], v[108:111]
	v_mfma_f32_16x16x32_bf16 v[108:111], v[128:131], v[190:193], v[108:111]
	v_mfma_f32_16x16x32_bf16 v[92:95], v[128:131], v[198:201], v[92:95]
	v_mfma_f32_16x16x32_bf16 v[92:95], v[132:135], v[202:205], v[92:95]
	v_mfma_f32_16x16x32_bf16 v[88:91], v[140:143], v[202:205], v[88:91]
	v_mfma_f32_16x16x32_bf16 v[88:91], v[136:139], v[198:201], v[88:91]
	v_mfma_f32_16x16x32_bf16 v[84:87], v[144:147], v[198:201], v[84:87]
	v_mfma_f32_16x16x32_bf16 v[84:87], v[148:151], v[202:205], v[84:87]
	v_mfma_f32_16x16x32_bf16 v[80:83], v[156:159], v[202:205], v[80:83]
	v_mfma_f32_16x16x32_bf16 v[80:83], v[152:155], v[198:201], v[80:83]
	v_mfma_f32_16x16x32_bf16 v[64:67], v[152:155], v[206:209], v[64:67]
	v_mfma_f32_16x16x32_bf16 v[64:67], v[156:159], v[210:213], v[64:67]
	v_mfma_f32_16x16x32_bf16 v[68:71], v[148:151], v[210:213], v[68:71]
	v_mfma_f32_16x16x32_bf16 v[68:71], v[144:147], v[206:209], v[68:71]
	v_mfma_f32_16x16x32_bf16 v[72:75], v[136:139], v[206:209], v[72:75]
	v_mfma_f32_16x16x32_bf16 v[72:75], v[140:143], v[210:213], v[72:75]
	v_mfma_f32_16x16x32_bf16 v[76:79], v[132:135], v[210:213], v[76:79]
	v_mfma_f32_16x16x32_bf16 v[76:79], v[128:131], v[206:209], v[76:79]
	s_barrier
	s_add_i32 s36, s36, s43
	s_add_u32 s98, s34, s20
	s_addc_u32 s99, s35, s21
	s_mov_b32 m0, s36
	ds_read_b128 v[160:163], v230 offset:16384
	ds_read_b128 v[164:167], v230 offset:17408
	ds_read_b128 v[190:193], v230 offset:18432
	ds_read_b128 v[194:197], v230 offset:19456
	ds_read_b128 v[198:201], v230 offset:20480
	ds_read_b128 v[202:205], v230 offset:21504
	ds_read_b128 v[206:209], v230 offset:22528
	ds_read_b128 v[210:213], v230 offset:23552
	global_load_lds_dwordx4 v168, s[34:35]
	s_add_i32 m0, s36, 0x2000
	s_add_u32 s36, s34, 0x100000
	s_addc_u32 s37, s35, 0
	s_add_i32 s58, s58, s43
	global_load_lds_dwordx4 v180, s[34:35]
	s_mov_b32 m0, s58
	s_nop 0
	global_load_lds_dwordx4 v168, s[36:37]
	s_add_i32 m0, s58, 0x2000
	s_nop 0
	global_load_lds_dwordx4 v180, s[36:37]
	s_add_u32 s100, s40, s20
	s_addc_u32 s101, s41, s21
	s_mov_b32 m0, s44
	s_nop 0
	global_load_lds_dwordx4 v184, s[40:41]
	s_mov_b32 m0, s45
	s_nop 0
	global_load_lds_dwordx4 v182, s[40:41]
	s_cmp_eq_u32 vcc_lo, 1
	s_cbranch_scc1 .Ltw_986_1
	s_waitcnt vmcnt(8)
.Ltw_986_1:
	s_waitcnt vmcnt(32)
	s_mov_b32 vcc_lo, 0
	s_waitcnt lgkmcnt(0)
	s_barrier
	v_mfma_f32_16x16x32_bf16 v[60:63], v[128:131], v[160:163], v[60:63]
	v_mfma_f32_16x16x32_bf16 v[60:63], v[132:135], v[164:167], v[60:63]
	v_mfma_f32_16x16x32_bf16 v[56:59], v[140:143], v[164:167], v[56:59]
	v_mfma_f32_16x16x32_bf16 v[56:59], v[136:139], v[160:163], v[56:59]
	v_mfma_f32_16x16x32_bf16 v[52:55], v[144:147], v[160:163], v[52:55]
	v_mfma_f32_16x16x32_bf16 v[52:55], v[148:151], v[164:167], v[52:55]
	v_mfma_f32_16x16x32_bf16 v[48:51], v[156:159], v[164:167], v[48:51]
	v_mfma_f32_16x16x32_bf16 v[48:51], v[152:155], v[160:163], v[48:51]
	v_mfma_f32_16x16x32_bf16 v[32:35], v[152:155], v[190:193], v[32:35]
	v_mfma_f32_16x16x32_bf16 v[32:35], v[156:159], v[194:197], v[32:35]
	v_mfma_f32_16x16x32_bf16 v[36:39], v[148:151], v[194:197], v[36:39]
	v_mfma_f32_16x16x32_bf16 v[36:39], v[144:147], v[190:193], v[36:39]
	v_mfma_f32_16x16x32_bf16 v[40:43], v[136:139], v[190:193], v[40:43]
	v_mfma_f32_16x16x32_bf16 v[40:43], v[140:143], v[194:197], v[40:43]
	v_mfma_f32_16x16x32_bf16 v[44:47], v[132:135], v[194:197], v[44:47]
	v_mfma_f32_16x16x32_bf16 v[44:47], v[128:131], v[190:193], v[44:47]
	v_mfma_f32_16x16x32_bf16 v[28:31], v[128:131], v[198:201], v[28:31]
	v_mfma_f32_16x16x32_bf16 v[28:31], v[132:135], v[202:205], v[28:31]
	v_mfma_f32_16x16x32_bf16 v[24:27], v[140:143], v[202:205], v[24:27]
	v_mfma_f32_16x16x32_bf16 v[24:27], v[136:139], v[198:201], v[24:27]
	v_mfma_f32_16x16x32_bf16 v[20:23], v[144:147], v[198:201], v[20:23]
	v_mfma_f32_16x16x32_bf16 v[20:23], v[148:151], v[202:205], v[20:23]
	v_mfma_f32_16x16x32_bf16 v[16:19], v[156:159], v[202:205], v[16:19]
	v_mfma_f32_16x16x32_bf16 v[16:19], v[152:155], v[198:201], v[16:19]
	v_mfma_f32_16x16x32_bf16 v[0:3], v[152:155], v[206:209], v[0:3]
	v_mfma_f32_16x16x32_bf16 v[0:3], v[156:159], v[210:213], v[0:3]
	v_mfma_f32_16x16x32_bf16 v[4:7], v[148:151], v[210:213], v[4:7]
	v_mfma_f32_16x16x32_bf16 v[4:7], v[144:147], v[206:209], v[4:7]
	v_mfma_f32_16x16x32_bf16 v[8:11], v[136:139], v[206:209], v[8:11]
	v_mfma_f32_16x16x32_bf16 v[8:11], v[140:143], v[210:213], v[8:11]
	v_mfma_f32_16x16x32_bf16 v[12:15], v[132:135], v[210:213], v[12:15]
	v_mfma_f32_16x16x32_bf16 v[12:15], v[128:131], v[206:209], v[12:15]
	s_barrier
	s_add_i32 s58, 0, 0x18000
	s_add_i32 s59, 0, 0x1c000
	v_add_u32_e32 v140, s58, v228
	v_add_u32_e32 v156, s59, v228
	ds_read_b128 v[128:131], v140
	ds_read_b128 v[132:135], v140 offset:1024
	ds_read_b128 v[136:139], v140 offset:2048
	ds_read_b128 v[140:143], v140 offset:3072
	ds_read_b128 v[144:147], v156
	ds_read_b128 v[148:151], v156 offset:1024
	ds_read_b128 v[152:155], v156 offset:2048
	ds_read_b128 v[156:159], v156 offset:3072
	s_add_u32 s36, s40, 0x100000
	s_addc_u32 s37, s41, 0
	s_mov_b32 m0, s46
	ds_read_b128 v[160:163], v230 offset:32768
	ds_read_b128 v[164:167], v230 offset:33792
	ds_read_b128 v[190:193], v230 offset:34816
	ds_read_b128 v[194:197], v230 offset:35840
	ds_read_b128 v[198:201], v230 offset:36864
	ds_read_b128 v[202:205], v230 offset:37888
	ds_read_b128 v[206:209], v230 offset:38912
	ds_read_b128 v[210:213], v230 offset:39936
	global_load_lds_dwordx4 v184, s[36:37]
	s_mov_b32 m0, s47
	s_nop 0
	global_load_lds_dwordx4 v182, s[36:37]
	s_waitcnt vmcnt(8)
	s_waitcnt lgkmcnt(0)
	s_barrier
	v_mfma_f32_16x16x32_bf16 v[124:127], v[128:131], v[160:163], v[124:127]
	v_mfma_f32_16x16x32_bf16 v[124:127], v[132:135], v[164:167], v[124:127]
	v_mfma_f32_16x16x32_bf16 v[120:123], v[140:143], v[164:167], v[120:123]
	v_mfma_f32_16x16x32_bf16 v[120:123], v[136:139], v[160:163], v[120:123]
	v_mfma_f32_16x16x32_bf16 v[116:119], v[144:147], v[160:163], v[116:119]
	v_mfma_f32_16x16x32_bf16 v[116:119], v[148:151], v[164:167], v[116:119]
	v_mfma_f32_16x16x32_bf16 v[112:115], v[156:159], v[164:167], v[112:115]
	v_mfma_f32_16x16x32_bf16 v[112:115], v[152:155], v[160:163], v[112:115]
	v_mfma_f32_16x16x32_bf16 v[96:99], v[152:155], v[190:193], v[96:99]
	v_mfma_f32_16x16x32_bf16 v[96:99], v[156:159], v[194:197], v[96:99]
	v_mfma_f32_16x16x32_bf16 v[100:103], v[148:151], v[194:197], v[100:103]
	v_mfma_f32_16x16x32_bf16 v[100:103], v[144:147], v[190:193], v[100:103]
	v_mfma_f32_16x16x32_bf16 v[104:107], v[136:139], v[190:193], v[104:107]
	v_mfma_f32_16x16x32_bf16 v[104:107], v[140:143], v[194:197], v[104:107]
	v_mfma_f32_16x16x32_bf16 v[108:111], v[132:135], v[194:197], v[108:111]
	v_mfma_f32_16x16x32_bf16 v[108:111], v[128:131], v[190:193], v[108:111]
	v_mfma_f32_16x16x32_bf16 v[92:95], v[128:131], v[198:201], v[92:95]
	v_mfma_f32_16x16x32_bf16 v[92:95], v[132:135], v[202:205], v[92:95]
	v_mfma_f32_16x16x32_bf16 v[88:91], v[140:143], v[202:205], v[88:91]
	v_mfma_f32_16x16x32_bf16 v[88:91], v[136:139], v[198:201], v[88:91]
	v_mfma_f32_16x16x32_bf16 v[84:87], v[144:147], v[198:201], v[84:87]
	v_mfma_f32_16x16x32_bf16 v[84:87], v[148:151], v[202:205], v[84:87]
	v_mfma_f32_16x16x32_bf16 v[80:83], v[156:159], v[202:205], v[80:83]
	v_mfma_f32_16x16x32_bf16 v[80:83], v[152:155], v[198:201], v[80:83]
	v_mfma_f32_16x16x32_bf16 v[64:67], v[152:155], v[206:209], v[64:67]
	v_mfma_f32_16x16x32_bf16 v[64:67], v[156:159], v[210:213], v[64:67]
	v_mfma_f32_16x16x32_bf16 v[68:71], v[148:151], v[210:213], v[68:71]
	v_mfma_f32_16x16x32_bf16 v[68:71], v[144:147], v[206:209], v[68:71]
	v_mfma_f32_16x16x32_bf16 v[72:75], v[136:139], v[206:209], v[72:75]
	v_mfma_f32_16x16x32_bf16 v[72:75], v[140:143], v[210:213], v[72:75]
	v_mfma_f32_16x16x32_bf16 v[76:79], v[132:135], v[210:213], v[76:79]
	v_mfma_f32_16x16x32_bf16 v[76:79], v[128:131], v[206:209], v[76:79]
	s_barrier
	s_add_i32 s36, s58, s43
	s_mov_b32 m0, s36
	ds_read_b128 v[160:163], v230 offset:49152
	ds_read_b128 v[164:167], v230 offset:50176
	ds_read_b128 v[190:193], v230 offset:51200
	ds_read_b128 v[194:197], v230 offset:52224
	ds_read_b128 v[198:201], v230 offset:53248
	ds_read_b128 v[202:205], v230 offset:54272
	ds_read_b128 v[206:209], v230 offset:55296
	ds_read_b128 v[210:213], v230 offset:56320
	global_load_lds_dwordx4 v168, s[98:99]
	s_add_i32 m0, s36, 0x2000
	s_add_u32 s34, s34, 0x100080
	s_addc_u32 s35, s35, 0
	s_add_i32 s36, s59, s43
	global_load_lds_dwordx4 v180, s[98:99]
	s_mov_b32 m0, s36
	s_nop 0
	global_load_lds_dwordx4 v168, s[34:35]
	s_add_i32 m0, s36, 0x2000
	s_nop 0
	global_load_lds_dwordx4 v180, s[34:35]
	s_mov_b32 m0, s50
	s_nop 0
	global_load_lds_dwordx4 v184, s[100:101]
	s_mov_b32 m0, s51
	s_nop 0
	global_load_lds_dwordx4 v182, s[100:101]
	s_waitcnt vmcnt(8)
	s_waitcnt lgkmcnt(0)
	s_barrier
	v_mfma_f32_16x16x32_bf16 v[60:63], v[128:131], v[160:163], v[60:63]
	v_mfma_f32_16x16x32_bf16 v[60:63], v[132:135], v[164:167], v[60:63]
	v_mfma_f32_16x16x32_bf16 v[56:59], v[140:143], v[164:167], v[56:59]
	v_mfma_f32_16x16x32_bf16 v[56:59], v[136:139], v[160:163], v[56:59]
	v_mfma_f32_16x16x32_bf16 v[52:55], v[144:147], v[160:163], v[52:55]
	v_mfma_f32_16x16x32_bf16 v[52:55], v[148:151], v[164:167], v[52:55]
	v_mfma_f32_16x16x32_bf16 v[48:51], v[156:159], v[164:167], v[48:51]
	v_mfma_f32_16x16x32_bf16 v[48:51], v[152:155], v[160:163], v[48:51]
	v_mfma_f32_16x16x32_bf16 v[32:35], v[152:155], v[190:193], v[32:35]
	v_mfma_f32_16x16x32_bf16 v[32:35], v[156:159], v[194:197], v[32:35]
	v_mfma_f32_16x16x32_bf16 v[36:39], v[148:151], v[194:197], v[36:39]
	v_mfma_f32_16x16x32_bf16 v[36:39], v[144:147], v[190:193], v[36:39]
	v_mfma_f32_16x16x32_bf16 v[40:43], v[136:139], v[190:193], v[40:43]
	v_mfma_f32_16x16x32_bf16 v[40:43], v[140:143], v[194:197], v[40:43]
	v_mfma_f32_16x16x32_bf16 v[44:47], v[132:135], v[194:197], v[44:47]
	v_mfma_f32_16x16x32_bf16 v[44:47], v[128:131], v[190:193], v[44:47]
	v_mfma_f32_16x16x32_bf16 v[28:31], v[128:131], v[198:201], v[28:31]
	v_mfma_f32_16x16x32_bf16 v[28:31], v[132:135], v[202:205], v[28:31]
	v_mfma_f32_16x16x32_bf16 v[24:27], v[140:143], v[202:205], v[24:27]
	v_mfma_f32_16x16x32_bf16 v[24:27], v[136:139], v[198:201], v[24:27]
	v_mfma_f32_16x16x32_bf16 v[20:23], v[144:147], v[198:201], v[20:23]
	v_mfma_f32_16x16x32_bf16 v[20:23], v[148:151], v[202:205], v[20:23]
	v_mfma_f32_16x16x32_bf16 v[16:19], v[156:159], v[202:205], v[16:19]
	v_mfma_f32_16x16x32_bf16 v[16:19], v[152:155], v[198:201], v[16:19]
	v_mfma_f32_16x16x32_bf16 v[0:3], v[152:155], v[206:209], v[0:3]
	v_mfma_f32_16x16x32_bf16 v[0:3], v[156:159], v[210:213], v[0:3]
	v_mfma_f32_16x16x32_bf16 v[4:7], v[148:151], v[210:213], v[4:7]
	v_mfma_f32_16x16x32_bf16 v[4:7], v[144:147], v[206:209], v[4:7]
	v_mfma_f32_16x16x32_bf16 v[8:11], v[136:139], v[206:209], v[8:11]
	v_mfma_f32_16x16x32_bf16 v[8:11], v[140:143], v[210:213], v[8:11]
	v_mfma_f32_16x16x32_bf16 v[12:15], v[132:135], v[210:213], v[12:15]
	v_mfma_f32_16x16x32_bf16 v[12:15], v[128:131], v[206:209], v[12:15]
	s_barrier
	s_add_i32 s57, s57, 2
	s_add_u32 s8, s8, 0x100
	s_addc_u32 s9, s9, 0
	s_add_u32 s55, s55, 0x100
	s_addc_u32 s56, s56, 0
	s_cmp_gt_u32 s57, 61
	s_cbranch_scc0 .LBB0_986
	s_mov_b32 vcc_lo, 1
	v_writelane_b32 v251, vcc_lo, 3
	s_and_b64 vcc, exec, s[12:13]
	s_cbranch_vccz .LBB0_989
	s_barrier

	.amdhsa_kernel _Z9trunk_fwd4Args
		.amdhsa_group_segment_fixed_size 0
		.amdhsa_private_segment_fixed_size 0
		.amdhsa_kernarg_size 464
		.amdhsa_user_sgpr_count 2
		.amdhsa_user_sgpr_dispatch_ptr 0
		.amdhsa_user_sgpr_queue_ptr 0
		.amdhsa_user_sgpr_kernarg_segment_ptr 1
		.amdhsa_user_sgpr_dispatch_id 0
		.amdhsa_user_sgpr_kernarg_preload_length 0
		.amdhsa_user_sgpr_kernarg_preload_offset 0
		.amdhsa_user_sgpr_private_segment_size 0
		.amdhsa_uses_dynamic_stack 0
		.amdhsa_enable_private_segment 0
		.amdhsa_system_sgpr_workgroup_id_x 1
		.amdhsa_system_sgpr_workgroup_id_y 0
		.amdhsa_system_sgpr_workgroup_id_z 0
		.amdhsa_system_sgpr_workgroup_info 0
		.amdhsa_system_vgpr_workitem_id 2
		.amdhsa_next_free_vgpr 252
		.amdhsa_next_free_sgpr 102
		.amdhsa_accum_offset 252
		.amdhsa_reserve_vcc 1
		.amdhsa_float_round_mode_32 0
		.amdhsa_float_round_mode_16_64 0
		.amdhsa_float_denorm_mode_32 3
		.amdhsa_float_denorm_mode_16_64 3
		.amdhsa_dx10_clamp 1
		.amdhsa_ieee_mode 1
		.amdhsa_fp16_overflow 0
		.amdhsa_tg_split 0
		.amdhsa_exception_fp_ieee_invalid_op 0
		.amdhsa_exception_fp_denorm_src 0
		.amdhsa_exception_fp_ieee_div_zero 0
		.amdhsa_exception_fp_ieee_overflow 0
		.amdhsa_exception_fp_ieee_underflow 0
		.amdhsa_exception_fp_ieee_inexact 0
		.amdhsa_exception_int_div_zero 0
	.end_amdhsa_kernel

amdhsa.kernels:
  - .agpr_count:     0
    .args:
      - .offset:         0
        .size:           208
        .value_kind:     by_value
      - .offset:         208
        .size:           4
        .value_kind:     hidden_block_count_x
      - .offset:         212
        .size:           4
        .value_kind:     hidden_block_count_y
      - .offset:         216
        .size:           4
        .value_kind:     hidden_block_count_z
      - .offset:         220
        .size:           2
        .value_kind:     hidden_group_size_x
      - .offset:         222
        .size:           2
        .value_kind:     hidden_group_size_y
      - .offset:         224
        .size:           2
        .value_kind:     hidden_group_size_z
      - .offset:         226
        .size:           2
        .value_kind:     hidden_remainder_x
      - .offset:         228
        .size:           2
        .value_kind:     hidden_remainder_y
      - .offset:         230
        .size:           2
        .value_kind:     hidden_remainder_z
      - .offset:         248
        .size:           8
        .value_kind:     hidden_global_offset_x
      - .offset:         256
        .size:           8
        .value_kind:     hidden_global_offset_y
      - .offset:         264
        .size:           8
        .value_kind:     hidden_global_offset_z
      - .offset:         272
        .size:           2
        .value_kind:     hidden_grid_dims
      - .offset:         296
        .size:           8
        .value_kind:     hidden_multigrid_sync_arg
      - .offset:         328
        .size:           4
        .value_kind:     hidden_dynamic_lds_size
    .group_segment_fixed_size: 0
    .kernarg_segment_align: 8
    .kernarg_segment_size: 464
    .language:       OpenCL C
    .language_version:
      - 2
      - 0
    .max_flat_workgroup_size: 512
    .name:           _Z9trunk_fwd4Args
    .private_segment_fixed_size: 0
    .sgpr_count:     108
    .sgpr_spill_count: 324
    .symbol:         _Z9trunk_fwd4Args.kd
    .uniform_work_group_size: 1
    .uses_dynamic_stack: false
    .vgpr_count:     252
    .vgpr_spill_count: 0
    .wavefront_size: 64
